# P0 modulation GEMV K loop fully unrolled with 40 weight loads in flight (was 4 loads + full wait per iteration); arithmetic order unchanged
# speedup vs baseline: 1.0869x; 1.0200x over previous
.LBB0_52:
	s_or_b64 exec, exec, s[6:7]
	s_add_i32 s4, s65, 0xfffff740
	s_cmpk_gt_u32 s4, 0x5f
	s_cselect_b64 s[6:7], -1, 0
	s_add_i32 s8, s65, 0xfffff6e0
	s_cmpk_lt_u32 s4, 0x60
	s_cselect_b32 s4, s4, s8
	s_lshl_b32 s4, s4, 5
	s_and_b64 s[8:9], s[6:7], exec
	s_cselect_b32 s10, 0xc00000, 0
	s_lshl_b64 s[8:9], s[4:5], 2
	s_add_u32 s8, s8, s10
	v_ashrrev_i32_e32 v1, 5, v15
	s_addc_u32 s9, s9, 0
	v_lshlrev_b32_e32 v5, 7, v1
	v_mov_b64_e32 v[6:7], s[8:9]
	v_mad_i64_i32 v[6:7], s[8:9], v5, s40, v[6:7]
	s_load_dwordx16 s[8:23], s[86:87], 0x40
	v_and_b32_e32 v4, 31, v15
	v_lshl_or_b32 v6, v4, 2, v6
	v_mov_b32_e32 v2, 0
	v_lshlrev_b32_e32 v12, 9, v1
	s_waitcnt lgkmcnt(0)
	v_mov_b32_e32 v8, 0
	v_mov_b32_e32 v9, v2
	v_mov_b32_e32 v10, 0
	v_mov_b32_e32 v11, v2
	global_load_dword v210, v6, s[12:13]
	s_add_u32 s10, s12, 0x3000
	s_addc_u32 s11, s13, 0
	global_load_dword v211, v6, s[10:11]
	s_add_u32 s8, s12, 0x6000
	s_addc_u32 s9, s13, 0
	global_load_dword v212, v6, s[8:9]
	s_add_u32 s10, s12, 0x9000
	s_addc_u32 s11, s13, 0
	global_load_dword v213, v6, s[10:11]
	s_add_u32 s8, s12, 0xc000
	s_addc_u32 s9, s13, 0
	global_load_dword v214, v6, s[8:9]
	s_add_u32 s10, s12, 0xf000
	s_addc_u32 s11, s13, 0
	global_load_dword v215, v6, s[10:11]
	s_add_u32 s8, s12, 0x12000
	s_addc_u32 s9, s13, 0
	global_load_dword v216, v6, s[8:9]
	s_add_u32 s10, s12, 0x15000
	s_addc_u32 s11, s13, 0
	global_load_dword v217, v6, s[10:11]
	s_add_u32 s8, s12, 0x18000
	s_addc_u32 s9, s13, 0
	global_load_dword v218, v6, s[8:9]
	s_add_u32 s10, s12, 0x1b000
	s_addc_u32 s11, s13, 0
	global_load_dword v219, v6, s[10:11]
	s_add_u32 s8, s12, 0x1e000
	s_addc_u32 s9, s13, 0
	global_load_dword v220, v6, s[8:9]
	s_add_u32 s10, s12, 0x21000
	s_addc_u32 s11, s13, 0
	global_load_dword v221, v6, s[10:11]
	s_add_u32 s8, s12, 0x24000
	s_addc_u32 s9, s13, 0
	global_load_dword v222, v6, s[8:9]
	s_add_u32 s10, s12, 0x27000
	s_addc_u32 s11, s13, 0
	global_load_dword v223, v6, s[10:11]
	s_add_u32 s8, s12, 0x2a000
	s_addc_u32 s9, s13, 0
	global_load_dword v224, v6, s[8:9]
	s_add_u32 s10, s12, 0x2d000
	s_addc_u32 s11, s13, 0
	global_load_dword v225, v6, s[10:11]
	s_add_u32 s8, s12, 0x30000
	s_addc_u32 s9, s13, 0
	global_load_dword v226, v6, s[8:9]
	s_add_u32 s10, s12, 0x33000
	s_addc_u32 s11, s13, 0
	global_load_dword v227, v6, s[10:11]
	s_add_u32 s8, s12, 0x36000
	s_addc_u32 s9, s13, 0
	global_load_dword v228, v6, s[8:9]
	s_add_u32 s10, s12, 0x39000
	s_addc_u32 s11, s13, 0
	global_load_dword v229, v6, s[10:11]
	s_add_u32 s8, s12, 0x3c000
	s_addc_u32 s9, s13, 0
	global_load_dword v230, v6, s[8:9]
	s_add_u32 s10, s12, 0x3f000
	s_addc_u32 s11, s13, 0
	global_load_dword v231, v6, s[10:11]
	s_add_u32 s8, s12, 0x42000
	s_addc_u32 s9, s13, 0
	global_load_dword v232, v6, s[8:9]
	s_add_u32 s10, s12, 0x45000
	s_addc_u32 s11, s13, 0
	global_load_dword v233, v6, s[10:11]
	s_add_u32 s8, s12, 0x48000
	s_addc_u32 s9, s13, 0
	global_load_dword v234, v6, s[8:9]
	s_add_u32 s10, s12, 0x4b000
	s_addc_u32 s11, s13, 0
	global_load_dword v235, v6, s[10:11]
	s_add_u32 s8, s12, 0x4e000
	s_addc_u32 s9, s13, 0
	global_load_dword v236, v6, s[8:9]
	s_add_u32 s10, s12, 0x51000
	s_addc_u32 s11, s13, 0
	global_load_dword v237, v6, s[10:11]
	s_add_u32 s8, s12, 0x54000
	s_addc_u32 s9, s13, 0
	global_load_dword v238, v6, s[8:9]
	s_add_u32 s10, s12, 0x57000
	s_addc_u32 s11, s13, 0
	global_load_dword v239, v6, s[10:11]
	s_add_u32 s8, s12, 0x5a000
	s_addc_u32 s9, s13, 0
	global_load_dword v240, v6, s[8:9]
	s_add_u32 s10, s12, 0x5d000
	s_addc_u32 s11, s13, 0
	global_load_dword v241, v6, s[10:11]
	s_add_u32 s8, s12, 0x60000
	s_addc_u32 s9, s13, 0
	global_load_dword v242, v6, s[8:9]
	s_add_u32 s10, s12, 0x63000
	s_addc_u32 s11, s13, 0
	global_load_dword v243, v6, s[10:11]
	s_add_u32 s8, s12, 0x66000
	s_addc_u32 s9, s13, 0
	global_load_dword v244, v6, s[8:9]
	s_add_u32 s10, s12, 0x69000
	s_addc_u32 s11, s13, 0
	global_load_dword v245, v6, s[10:11]
	s_add_u32 s8, s12, 0x6c000
	s_addc_u32 s9, s13, 0
	global_load_dword v246, v6, s[8:9]
	s_add_u32 s10, s12, 0x6f000
	s_addc_u32 s11, s13, 0
	global_load_dword v247, v6, s[10:11]
	s_add_u32 s8, s12, 0x72000
	s_addc_u32 s9, s13, 0
	global_load_dword v248, v6, s[8:9]
	s_add_u32 s10, s12, 0x75000
	s_addc_u32 s11, s13, 0
	global_load_dword v249, v6, s[10:11]
	s_barrier
	ds_read_b128 v[16:19], v12
	ds_read_b128 v[20:23], v12 offset:4096
	ds_read_b128 v[24:27], v12 offset:8192
	ds_read_b128 v[28:31], v12 offset:12288
	ds_read_b128 v[32:35], v12 offset:16384
	s_waitcnt lgkmcnt(4)
	v_mov_b32_e32 v44, v16
	s_waitcnt lgkmcnt(3)
	v_mov_b32_e32 v45, v20
	s_waitcnt lgkmcnt(2)
	v_mov_b32_e32 v46, v24
	s_waitcnt lgkmcnt(1)
	v_mov_b32_e32 v47, v28
	v_mov_b32_e32 v20, v17
	v_mov_b32_e32 v28, v25
	v_mov_b32_e32 v16, v18
	v_mov_b32_e32 v17, v22
	v_mov_b32_e32 v24, v26
	v_mov_b32_e32 v25, v30
	v_mov_b32_e32 v22, v19
	v_mov_b32_e32 v30, v27
	v_add_u32_e32 v12, 16, v12
	s_waitcnt vmcnt(39)
	v_pk_fma_f32 v[8:9], v[210:211], v[44:45], v[8:9] op_sel_hi:[0,1,1]
	v_pk_fma_f32 v[10:11], v[210:211], v[46:47], v[10:11] op_sel_hi:[0,1,1]
	s_waitcnt lgkmcnt(0)
	v_fmac_f32_e32 v2, v210, v32
	s_waitcnt vmcnt(38)
	v_pk_fma_f32 v[8:9], v[210:211], v[20:21], v[8:9] op_sel:[1,0,0] op_sel_hi:[1,1,1]
	v_pk_fma_f32 v[10:11], v[210:211], v[28:29], v[10:11] op_sel:[1,0,0] op_sel_hi:[1,1,1]
	v_fmac_f32_e32 v2, v211, v33
	s_waitcnt vmcnt(37)
	v_pk_fma_f32 v[8:9], v[212:213], v[16:17], v[8:9] op_sel_hi:[0,1,1]
	v_pk_fma_f32 v[10:11], v[212:213], v[24:25], v[10:11] op_sel_hi:[0,1,1]
	v_fmac_f32_e32 v2, v212, v34
	s_waitcnt vmcnt(36)
	v_pk_fma_f32 v[8:9], v[212:213], v[22:23], v[8:9] op_sel:[1,0,0] op_sel_hi:[1,1,1]
	v_pk_fma_f32 v[10:11], v[212:213], v[30:31], v[10:11] op_sel:[1,0,0] op_sel_hi:[1,1,1]
	v_fmac_f32_e32 v2, v213, v35
	s_add_u32 s8, s12, 0x78000
	s_addc_u32 s9, s13, 0
	global_load_dword v210, v6, s[8:9]
	s_add_u32 s10, s12, 0x7b000
	s_addc_u32 s11, s13, 0
	global_load_dword v211, v6, s[10:11]
	s_add_u32 s8, s12, 0x7e000
	s_addc_u32 s9, s13, 0
	global_load_dword v212, v6, s[8:9]
	s_add_u32 s10, s12, 0x81000
	s_addc_u32 s11, s13, 0
	global_load_dword v213, v6, s[10:11]
	ds_read_b128 v[16:19], v12
	ds_read_b128 v[20:23], v12 offset:4096
	ds_read_b128 v[24:27], v12 offset:8192
	ds_read_b128 v[28:31], v12 offset:12288
	ds_read_b128 v[32:35], v12 offset:16384
	s_waitcnt lgkmcnt(4)
	v_mov_b32_e32 v44, v16
	s_waitcnt lgkmcnt(3)
	v_mov_b32_e32 v45, v20
	s_waitcnt lgkmcnt(2)
	v_mov_b32_e32 v46, v24
	s_waitcnt lgkmcnt(1)
	v_mov_b32_e32 v47, v28
	v_mov_b32_e32 v20, v17
	v_mov_b32_e32 v28, v25
	v_mov_b32_e32 v16, v18
	v_mov_b32_e32 v17, v22
	v_mov_b32_e32 v24, v26
	v_mov_b32_e32 v25, v30
	v_mov_b32_e32 v22, v19
	v_mov_b32_e32 v30, v27
	v_add_u32_e32 v12, 16, v12
	s_waitcnt vmcnt(39)
	v_pk_fma_f32 v[8:9], v[214:215], v[44:45], v[8:9] op_sel_hi:[0,1,1]
	v_pk_fma_f32 v[10:11], v[214:215], v[46:47], v[10:11] op_sel_hi:[0,1,1]
	s_waitcnt lgkmcnt(0)
	v_fmac_f32_e32 v2, v214, v32
	s_waitcnt vmcnt(38)
	v_pk_fma_f32 v[8:9], v[214:215], v[20:21], v[8:9] op_sel:[1,0,0] op_sel_hi:[1,1,1]
	v_pk_fma_f32 v[10:11], v[214:215], v[28:29], v[10:11] op_sel:[1,0,0] op_sel_hi:[1,1,1]
	v_fmac_f32_e32 v2, v215, v33
	s_waitcnt vmcnt(37)
	v_pk_fma_f32 v[8:9], v[216:217], v[16:17], v[8:9] op_sel_hi:[0,1,1]
	v_pk_fma_f32 v[10:11], v[216:217], v[24:25], v[10:11] op_sel_hi:[0,1,1]
	v_fmac_f32_e32 v2, v216, v34
	s_waitcnt vmcnt(36)
	v_pk_fma_f32 v[8:9], v[216:217], v[22:23], v[8:9] op_sel:[1,0,0] op_sel_hi:[1,1,1]
	v_pk_fma_f32 v[10:11], v[216:217], v[30:31], v[10:11] op_sel:[1,0,0] op_sel_hi:[1,1,1]
	v_fmac_f32_e32 v2, v217, v35
	s_add_u32 s8, s12, 0x84000
	s_addc_u32 s9, s13, 0
	global_load_dword v214, v6, s[8:9]
	s_add_u32 s10, s12, 0x87000
	s_addc_u32 s11, s13, 0
	global_load_dword v215, v6, s[10:11]
	s_add_u32 s8, s12, 0x8a000
	s_addc_u32 s9, s13, 0
	global_load_dword v216, v6, s[8:9]
	s_add_u32 s10, s12, 0x8d000
	s_addc_u32 s11, s13, 0
	global_load_dword v217, v6, s[10:11]
	ds_read_b128 v[16:19], v12
	ds_read_b128 v[20:23], v12 offset:4096
	ds_read_b128 v[24:27], v12 offset:8192
	ds_read_b128 v[28:31], v12 offset:12288
	ds_read_b128 v[32:35], v12 offset:16384
	s_waitcnt lgkmcnt(4)
	v_mov_b32_e32 v44, v16
	s_waitcnt lgkmcnt(3)
	v_mov_b32_e32 v45, v20
	s_waitcnt lgkmcnt(2)
	v_mov_b32_e32 v46, v24
	s_waitcnt lgkmcnt(1)
	v_mov_b32_e32 v47, v28
	v_mov_b32_e32 v20, v17
	v_mov_b32_e32 v28, v25
	v_mov_b32_e32 v16, v18
	v_mov_b32_e32 v17, v22
	v_mov_b32_e32 v24, v26
	v_mov_b32_e32 v25, v30
	v_mov_b32_e32 v22, v19
	v_mov_b32_e32 v30, v27
	v_add_u32_e32 v12, 16, v12
	s_waitcnt vmcnt(39)
	v_pk_fma_f32 v[8:9], v[218:219], v[44:45], v[8:9] op_sel_hi:[0,1,1]
	v_pk_fma_f32 v[10:11], v[218:219], v[46:47], v[10:11] op_sel_hi:[0,1,1]
	s_waitcnt lgkmcnt(0)
	v_fmac_f32_e32 v2, v218, v32
	s_waitcnt vmcnt(38)
	v_pk_fma_f32 v[8:9], v[218:219], v[20:21], v[8:9] op_sel:[1,0,0] op_sel_hi:[1,1,1]
	v_pk_fma_f32 v[10:11], v[218:219], v[28:29], v[10:11] op_sel:[1,0,0] op_sel_hi:[1,1,1]
	v_fmac_f32_e32 v2, v219, v33
	s_waitcnt vmcnt(37)
	v_pk_fma_f32 v[8:9], v[220:221], v[16:17], v[8:9] op_sel_hi:[0,1,1]
	v_pk_fma_f32 v[10:11], v[220:221], v[24:25], v[10:11] op_sel_hi:[0,1,1]
	v_fmac_f32_e32 v2, v220, v34
	s_waitcnt vmcnt(36)
	v_pk_fma_f32 v[8:9], v[220:221], v[22:23], v[8:9] op_sel:[1,0,0] op_sel_hi:[1,1,1]
	v_pk_fma_f32 v[10:11], v[220:221], v[30:31], v[10:11] op_sel:[1,0,0] op_sel_hi:[1,1,1]
	v_fmac_f32_e32 v2, v221, v35
	s_add_u32 s8, s12, 0x90000
	s_addc_u32 s9, s13, 0
	global_load_dword v218, v6, s[8:9]
	s_add_u32 s10, s12, 0x93000
	s_addc_u32 s11, s13, 0
	global_load_dword v219, v6, s[10:11]
	s_add_u32 s8, s12, 0x96000
	s_addc_u32 s9, s13, 0
	global_load_dword v220, v6, s[8:9]
	s_add_u32 s10, s12, 0x99000
	s_addc_u32 s11, s13, 0
	global_load_dword v221, v6, s[10:11]
	ds_read_b128 v[16:19], v12
	ds_read_b128 v[20:23], v12 offset:4096
	ds_read_b128 v[24:27], v12 offset:8192
	ds_read_b128 v[28:31], v12 offset:12288
	ds_read_b128 v[32:35], v12 offset:16384
	s_waitcnt lgkmcnt(4)
	v_mov_b32_e32 v44, v16
	s_waitcnt lgkmcnt(3)
	v_mov_b32_e32 v45, v20
	s_waitcnt lgkmcnt(2)
	v_mov_b32_e32 v46, v24
	s_waitcnt lgkmcnt(1)
	v_mov_b32_e32 v47, v28
	v_mov_b32_e32 v20, v17
	v_mov_b32_e32 v28, v25
	v_mov_b32_e32 v16, v18
	v_mov_b32_e32 v17, v22
	v_mov_b32_e32 v24, v26
	v_mov_b32_e32 v25, v30
	v_mov_b32_e32 v22, v19
	v_mov_b32_e32 v30, v27
	v_add_u32_e32 v12, 16, v12
	s_waitcnt vmcnt(39)
	v_pk_fma_f32 v[8:9], v[222:223], v[44:45], v[8:9] op_sel_hi:[0,1,1]
	v_pk_fma_f32 v[10:11], v[222:223], v[46:47], v[10:11] op_sel_hi:[0,1,1]
	s_waitcnt lgkmcnt(0)
	v_fmac_f32_e32 v2, v222, v32
	s_waitcnt vmcnt(38)
	v_pk_fma_f32 v[8:9], v[222:223], v[20:21], v[8:9] op_sel:[1,0,0] op_sel_hi:[1,1,1]
	v_pk_fma_f32 v[10:11], v[222:223], v[28:29], v[10:11] op_sel:[1,0,0] op_sel_hi:[1,1,1]
	v_fmac_f32_e32 v2, v223, v33
	s_waitcnt vmcnt(37)
	v_pk_fma_f32 v[8:9], v[224:225], v[16:17], v[8:9] op_sel_hi:[0,1,1]
	v_pk_fma_f32 v[10:11], v[224:225], v[24:25], v[10:11] op_sel_hi:[0,1,1]
	v_fmac_f32_e32 v2, v224, v34
	s_waitcnt vmcnt(36)
	v_pk_fma_f32 v[8:9], v[224:225], v[22:23], v[8:9] op_sel:[1,0,0] op_sel_hi:[1,1,1]
	v_pk_fma_f32 v[10:11], v[224:225], v[30:31], v[10:11] op_sel:[1,0,0] op_sel_hi:[1,1,1]
	v_fmac_f32_e32 v2, v225, v35
	s_add_u32 s8, s12, 0x9c000
	s_addc_u32 s9, s13, 0
	global_load_dword v222, v6, s[8:9]
	s_add_u32 s10, s12, 0x9f000
	s_addc_u32 s11, s13, 0
	global_load_dword v223, v6, s[10:11]
	s_add_u32 s8, s12, 0xa2000
	s_addc_u32 s9, s13, 0
	global_load_dword v224, v6, s[8:9]
	s_add_u32 s10, s12, 0xa5000
	s_addc_u32 s11, s13, 0
	global_load_dword v225, v6, s[10:11]
	ds_read_b128 v[16:19], v12
	ds_read_b128 v[20:23], v12 offset:4096
	ds_read_b128 v[24:27], v12 offset:8192
	ds_read_b128 v[28:31], v12 offset:12288
	ds_read_b128 v[32:35], v12 offset:16384
	s_waitcnt lgkmcnt(4)
	v_mov_b32_e32 v44, v16
	s_waitcnt lgkmcnt(3)
	v_mov_b32_e32 v45, v20
	s_waitcnt lgkmcnt(2)
	v_mov_b32_e32 v46, v24
	s_waitcnt lgkmcnt(1)
	v_mov_b32_e32 v47, v28
	v_mov_b32_e32 v20, v17
	v_mov_b32_e32 v28, v25
	v_mov_b32_e32 v16, v18
	v_mov_b32_e32 v17, v22
	v_mov_b32_e32 v24, v26
	v_mov_b32_e32 v25, v30
	v_mov_b32_e32 v22, v19
	v_mov_b32_e32 v30, v27
	v_add_u32_e32 v12, 16, v12
	s_waitcnt vmcnt(39)
	v_pk_fma_f32 v[8:9], v[226:227], v[44:45], v[8:9] op_sel_hi:[0,1,1]
	v_pk_fma_f32 v[10:11], v[226:227], v[46:47], v[10:11] op_sel_hi:[0,1,1]
	s_waitcnt lgkmcnt(0)
	v_fmac_f32_e32 v2, v226, v32
	s_waitcnt vmcnt(38)
	v_pk_fma_f32 v[8:9], v[226:227], v[20:21], v[8:9] op_sel:[1,0,0] op_sel_hi:[1,1,1]
	v_pk_fma_f32 v[10:11], v[226:227], v[28:29], v[10:11] op_sel:[1,0,0] op_sel_hi:[1,1,1]
	v_fmac_f32_e32 v2, v227, v33
	s_waitcnt vmcnt(37)
	v_pk_fma_f32 v[8:9], v[228:229], v[16:17], v[8:9] op_sel_hi:[0,1,1]
	v_pk_fma_f32 v[10:11], v[228:229], v[24:25], v[10:11] op_sel_hi:[0,1,1]
	v_fmac_f32_e32 v2, v228, v34
	s_waitcnt vmcnt(36)
	v_pk_fma_f32 v[8:9], v[228:229], v[22:23], v[8:9] op_sel:[1,0,0] op_sel_hi:[1,1,1]
	v_pk_fma_f32 v[10:11], v[228:229], v[30:31], v[10:11] op_sel:[1,0,0] op_sel_hi:[1,1,1]
	v_fmac_f32_e32 v2, v229, v35
	s_add_u32 s8, s12, 0xa8000
	s_addc_u32 s9, s13, 0
	global_load_dword v226, v6, s[8:9]
	s_add_u32 s10, s12, 0xab000
	s_addc_u32 s11, s13, 0
	global_load_dword v227, v6, s[10:11]
	s_add_u32 s8, s12, 0xae000
	s_addc_u32 s9, s13, 0
	global_load_dword v228, v6, s[8:9]
	s_add_u32 s10, s12, 0xb1000
	s_addc_u32 s11, s13, 0
	global_load_dword v229, v6, s[10:11]
	ds_read_b128 v[16:19], v12
	ds_read_b128 v[20:23], v12 offset:4096
	ds_read_b128 v[24:27], v12 offset:8192
	ds_read_b128 v[28:31], v12 offset:12288
	ds_read_b128 v[32:35], v12 offset:16384
	s_waitcnt lgkmcnt(4)
	v_mov_b32_e32 v44, v16
	s_waitcnt lgkmcnt(3)
	v_mov_b32_e32 v45, v20
	s_waitcnt lgkmcnt(2)
	v_mov_b32_e32 v46, v24
	s_waitcnt lgkmcnt(1)
	v_mov_b32_e32 v47, v28
	v_mov_b32_e32 v20, v17
	v_mov_b32_e32 v28, v25
	v_mov_b32_e32 v16, v18
	v_mov_b32_e32 v17, v22
	v_mov_b32_e32 v24, v26
	v_mov_b32_e32 v25, v30
	v_mov_b32_e32 v22, v19
	v_mov_b32_e32 v30, v27
	v_add_u32_e32 v12, 16, v12
	s_waitcnt vmcnt(39)
	v_pk_fma_f32 v[8:9], v[230:231], v[44:45], v[8:9] op_sel_hi:[0,1,1]
	v_pk_fma_f32 v[10:11], v[230:231], v[46:47], v[10:11] op_sel_hi:[0,1,1]
	s_waitcnt lgkmcnt(0)
	v_fmac_f32_e32 v2, v230, v32
	s_waitcnt vmcnt(38)
	v_pk_fma_f32 v[8:9], v[230:231], v[20:21], v[8:9] op_sel:[1,0,0] op_sel_hi:[1,1,1]
	v_pk_fma_f32 v[10:11], v[230:231], v[28:29], v[10:11] op_sel:[1,0,0] op_sel_hi:[1,1,1]
	v_fmac_f32_e32 v2, v231, v33
	s_waitcnt vmcnt(37)
	v_pk_fma_f32 v[8:9], v[232:233], v[16:17], v[8:9] op_sel_hi:[0,1,1]
	v_pk_fma_f32 v[10:11], v[232:233], v[24:25], v[10:11] op_sel_hi:[0,1,1]
	v_fmac_f32_e32 v2, v232, v34
	s_waitcnt vmcnt(36)
	v_pk_fma_f32 v[8:9], v[232:233], v[22:23], v[8:9] op_sel:[1,0,0] op_sel_hi:[1,1,1]
	v_pk_fma_f32 v[10:11], v[232:233], v[30:31], v[10:11] op_sel:[1,0,0] op_sel_hi:[1,1,1]
	v_fmac_f32_e32 v2, v233, v35
	s_add_u32 s8, s12, 0xb4000
	s_addc_u32 s9, s13, 0
	global_load_dword v230, v6, s[8:9]
	s_add_u32 s10, s12, 0xb7000
	s_addc_u32 s11, s13, 0
	global_load_dword v231, v6, s[10:11]
	s_add_u32 s8, s12, 0xba000
	s_addc_u32 s9, s13, 0
	global_load_dword v232, v6, s[8:9]
	s_add_u32 s10, s12, 0xbd000
	s_addc_u32 s11, s13, 0
	global_load_dword v233, v6, s[10:11]
	ds_read_b128 v[16:19], v12
	ds_read_b128 v[20:23], v12 offset:4096
	ds_read_b128 v[24:27], v12 offset:8192
	ds_read_b128 v[28:31], v12 offset:12288
	ds_read_b128 v[32:35], v12 offset:16384
	s_waitcnt lgkmcnt(4)
	v_mov_b32_e32 v44, v16
	s_waitcnt lgkmcnt(3)
	v_mov_b32_e32 v45, v20
	s_waitcnt lgkmcnt(2)
	v_mov_b32_e32 v46, v24
	s_waitcnt lgkmcnt(1)
	v_mov_b32_e32 v47, v28
	v_mov_b32_e32 v20, v17
	v_mov_b32_e32 v28, v25
	v_mov_b32_e32 v16, v18
	v_mov_b32_e32 v17, v22
	v_mov_b32_e32 v24, v26
	v_mov_b32_e32 v25, v30
	v_mov_b32_e32 v22, v19
	v_mov_b32_e32 v30, v27
	v_add_u32_e32 v12, 16, v12
	s_waitcnt vmcnt(39)
	v_pk_fma_f32 v[8:9], v[234:235], v[44:45], v[8:9] op_sel_hi:[0,1,1]
	v_pk_fma_f32 v[10:11], v[234:235], v[46:47], v[10:11] op_sel_hi:[0,1,1]
	s_waitcnt lgkmcnt(0)
	v_fmac_f32_e32 v2, v234, v32
	s_waitcnt vmcnt(38)
	v_pk_fma_f32 v[8:9], v[234:235], v[20:21], v[8:9] op_sel:[1,0,0] op_sel_hi:[1,1,1]
	v_pk_fma_f32 v[10:11], v[234:235], v[28:29], v[10:11] op_sel:[1,0,0] op_sel_hi:[1,1,1]
	v_fmac_f32_e32 v2, v235, v33
	s_waitcnt vmcnt(37)
	v_pk_fma_f32 v[8:9], v[236:237], v[16:17], v[8:9] op_sel_hi:[0,1,1]
	v_pk_fma_f32 v[10:11], v[236:237], v[24:25], v[10:11] op_sel_hi:[0,1,1]
	v_fmac_f32_e32 v2, v236, v34
	s_waitcnt vmcnt(36)
	v_pk_fma_f32 v[8:9], v[236:237], v[22:23], v[8:9] op_sel:[1,0,0] op_sel_hi:[1,1,1]
	v_pk_fma_f32 v[10:11], v[236:237], v[30:31], v[10:11] op_sel:[1,0,0] op_sel_hi:[1,1,1]
	v_fmac_f32_e32 v2, v237, v35
	s_add_u32 s8, s12, 0xc0000
	s_addc_u32 s9, s13, 0
	global_load_dword v234, v6, s[8:9]
	s_add_u32 s10, s12, 0xc3000
	s_addc_u32 s11, s13, 0
	global_load_dword v235, v6, s[10:11]
	s_add_u32 s8, s12, 0xc6000
	s_addc_u32 s9, s13, 0
	global_load_dword v236, v6, s[8:9]
	s_add_u32 s10, s12, 0xc9000
	s_addc_u32 s11, s13, 0
	global_load_dword v237, v6, s[10:11]
	ds_read_b128 v[16:19], v12
	ds_read_b128 v[20:23], v12 offset:4096
	ds_read_b128 v[24:27], v12 offset:8192
	ds_read_b128 v[28:31], v12 offset:12288
	ds_read_b128 v[32:35], v12 offset:16384
	s_waitcnt lgkmcnt(4)
	v_mov_b32_e32 v44, v16
	s_waitcnt lgkmcnt(3)
	v_mov_b32_e32 v45, v20
	s_waitcnt lgkmcnt(2)
	v_mov_b32_e32 v46, v24
	s_waitcnt lgkmcnt(1)
	v_mov_b32_e32 v47, v28
	v_mov_b32_e32 v20, v17
	v_mov_b32_e32 v28, v25
	v_mov_b32_e32 v16, v18
	v_mov_b32_e32 v17, v22
	v_mov_b32_e32 v24, v26
	v_mov_b32_e32 v25, v30
	v_mov_b32_e32 v22, v19
	v_mov_b32_e32 v30, v27
	v_add_u32_e32 v12, 16, v12
	s_waitcnt vmcnt(39)
	v_pk_fma_f32 v[8:9], v[238:239], v[44:45], v[8:9] op_sel_hi:[0,1,1]
	v_pk_fma_f32 v[10:11], v[238:239], v[46:47], v[10:11] op_sel_hi:[0,1,1]
	s_waitcnt lgkmcnt(0)
	v_fmac_f32_e32 v2, v238, v32
	s_waitcnt vmcnt(38)
	v_pk_fma_f32 v[8:9], v[238:239], v[20:21], v[8:9] op_sel:[1,0,0] op_sel_hi:[1,1,1]
	v_pk_fma_f32 v[10:11], v[238:239], v[28:29], v[10:11] op_sel:[1,0,0] op_sel_hi:[1,1,1]
	v_fmac_f32_e32 v2, v239, v33
	s_waitcnt vmcnt(37)
	v_pk_fma_f32 v[8:9], v[240:241], v[16:17], v[8:9] op_sel_hi:[0,1,1]
	v_pk_fma_f32 v[10:11], v[240:241], v[24:25], v[10:11] op_sel_hi:[0,1,1]
	v_fmac_f32_e32 v2, v240, v34
	s_waitcnt vmcnt(36)
	v_pk_fma_f32 v[8:9], v[240:241], v[22:23], v[8:9] op_sel:[1,0,0] op_sel_hi:[1,1,1]
	v_pk_fma_f32 v[10:11], v[240:241], v[30:31], v[10:11] op_sel:[1,0,0] op_sel_hi:[1,1,1]
	v_fmac_f32_e32 v2, v241, v35
	s_add_u32 s8, s12, 0xcc000
	s_addc_u32 s9, s13, 0
	global_load_dword v238, v6, s[8:9]
	s_add_u32 s10, s12, 0xcf000
	s_addc_u32 s11, s13, 0
	global_load_dword v239, v6, s[10:11]
	s_add_u32 s8, s12, 0xd2000
	s_addc_u32 s9, s13, 0
	global_load_dword v240, v6, s[8:9]
	s_add_u32 s10, s12, 0xd5000
	s_addc_u32 s11, s13, 0
	global_load_dword v241, v6, s[10:11]
	ds_read_b128 v[16:19], v12
	ds_read_b128 v[20:23], v12 offset:4096
	ds_read_b128 v[24:27], v12 offset:8192
	ds_read_b128 v[28:31], v12 offset:12288
	ds_read_b128 v[32:35], v12 offset:16384
	s_waitcnt lgkmcnt(4)
	v_mov_b32_e32 v44, v16
	s_waitcnt lgkmcnt(3)
	v_mov_b32_e32 v45, v20
	s_waitcnt lgkmcnt(2)
	v_mov_b32_e32 v46, v24
	s_waitcnt lgkmcnt(1)
	v_mov_b32_e32 v47, v28
	v_mov_b32_e32 v20, v17
	v_mov_b32_e32 v28, v25
	v_mov_b32_e32 v16, v18
	v_mov_b32_e32 v17, v22
	v_mov_b32_e32 v24, v26
	v_mov_b32_e32 v25, v30
	v_mov_b32_e32 v22, v19
	v_mov_b32_e32 v30, v27
	v_add_u32_e32 v12, 16, v12
	s_waitcnt vmcnt(39)
	v_pk_fma_f32 v[8:9], v[242:243], v[44:45], v[8:9] op_sel_hi:[0,1,1]
	v_pk_fma_f32 v[10:11], v[242:243], v[46:47], v[10:11] op_sel_hi:[0,1,1]
	s_waitcnt lgkmcnt(0)
	v_fmac_f32_e32 v2, v242, v32
	s_waitcnt vmcnt(38)
	v_pk_fma_f32 v[8:9], v[242:243], v[20:21], v[8:9] op_sel:[1,0,0] op_sel_hi:[1,1,1]
	v_pk_fma_f32 v[10:11], v[242:243], v[28:29], v[10:11] op_sel:[1,0,0] op_sel_hi:[1,1,1]
	v_fmac_f32_e32 v2, v243, v33
	s_waitcnt vmcnt(37)
	v_pk_fma_f32 v[8:9], v[244:245], v[16:17], v[8:9] op_sel_hi:[0,1,1]
	v_pk_fma_f32 v[10:11], v[244:245], v[24:25], v[10:11] op_sel_hi:[0,1,1]
	v_fmac_f32_e32 v2, v244, v34
	s_waitcnt vmcnt(36)
	v_pk_fma_f32 v[8:9], v[244:245], v[22:23], v[8:9] op_sel:[1,0,0] op_sel_hi:[1,1,1]
	v_pk_fma_f32 v[10:11], v[244:245], v[30:31], v[10:11] op_sel:[1,0,0] op_sel_hi:[1,1,1]
	v_fmac_f32_e32 v2, v245, v35
	s_add_u32 s8, s12, 0xd8000
	s_addc_u32 s9, s13, 0
	global_load_dword v242, v6, s[8:9]
	s_add_u32 s10, s12, 0xdb000
	s_addc_u32 s11, s13, 0
	global_load_dword v243, v6, s[10:11]
	s_add_u32 s8, s12, 0xde000
	s_addc_u32 s9, s13, 0
	global_load_dword v244, v6, s[8:9]
	s_add_u32 s10, s12, 0xe1000
	s_addc_u32 s11, s13, 0
	global_load_dword v245, v6, s[10:11]
	ds_read_b128 v[16:19], v12
	ds_read_b128 v[20:23], v12 offset:4096
	ds_read_b128 v[24:27], v12 offset:8192
	ds_read_b128 v[28:31], v12 offset:12288
	ds_read_b128 v[32:35], v12 offset:16384
	s_waitcnt lgkmcnt(4)
	v_mov_b32_e32 v44, v16
	s_waitcnt lgkmcnt(3)
	v_mov_b32_e32 v45, v20
	s_waitcnt lgkmcnt(2)
	v_mov_b32_e32 v46, v24
	s_waitcnt lgkmcnt(1)
	v_mov_b32_e32 v47, v28
	v_mov_b32_e32 v20, v17
	v_mov_b32_e32 v28, v25
	v_mov_b32_e32 v16, v18
	v_mov_b32_e32 v17, v22
	v_mov_b32_e32 v24, v26
	v_mov_b32_e32 v25, v30
	v_mov_b32_e32 v22, v19
	v_mov_b32_e32 v30, v27
	v_add_u32_e32 v12, 16, v12
	s_waitcnt vmcnt(39)
	v_pk_fma_f32 v[8:9], v[246:247], v[44:45], v[8:9] op_sel_hi:[0,1,1]
	v_pk_fma_f32 v[10:11], v[246:247], v[46:47], v[10:11] op_sel_hi:[0,1,1]
	s_waitcnt lgkmcnt(0)
	v_fmac_f32_e32 v2, v246, v32
	s_waitcnt vmcnt(38)
	v_pk_fma_f32 v[8:9], v[246:247], v[20:21], v[8:9] op_sel:[1,0,0] op_sel_hi:[1,1,1]
	v_pk_fma_f32 v[10:11], v[246:247], v[28:29], v[10:11] op_sel:[1,0,0] op_sel_hi:[1,1,1]
	v_fmac_f32_e32 v2, v247, v33
	s_waitcnt vmcnt(37)
	v_pk_fma_f32 v[8:9], v[248:249], v[16:17], v[8:9] op_sel_hi:[0,1,1]
	v_pk_fma_f32 v[10:11], v[248:249], v[24:25], v[10:11] op_sel_hi:[0,1,1]
	v_fmac_f32_e32 v2, v248, v34
	s_waitcnt vmcnt(36)
	v_pk_fma_f32 v[8:9], v[248:249], v[22:23], v[8:9] op_sel:[1,0,0] op_sel_hi:[1,1,1]
	v_pk_fma_f32 v[10:11], v[248:249], v[30:31], v[10:11] op_sel:[1,0,0] op_sel_hi:[1,1,1]
	v_fmac_f32_e32 v2, v249, v35
	s_add_u32 s8, s12, 0xe4000
	s_addc_u32 s9, s13, 0
	global_load_dword v246, v6, s[8:9]
	s_add_u32 s10, s12, 0xe7000
	s_addc_u32 s11, s13, 0
	global_load_dword v247, v6, s[10:11]
	s_add_u32 s8, s12, 0xea000
	s_addc_u32 s9, s13, 0
	global_load_dword v248, v6, s[8:9]
	s_add_u32 s10, s12, 0xed000
	s_addc_u32 s11, s13, 0
	global_load_dword v249, v6, s[10:11]
	ds_read_b128 v[16:19], v12
	ds_read_b128 v[20:23], v12 offset:4096
	ds_read_b128 v[24:27], v12 offset:8192
	ds_read_b128 v[28:31], v12 offset:12288
	ds_read_b128 v[32:35], v12 offset:16384
	s_waitcnt lgkmcnt(4)
	v_mov_b32_e32 v44, v16
	s_waitcnt lgkmcnt(3)
	v_mov_b32_e32 v45, v20
	s_waitcnt lgkmcnt(2)
	v_mov_b32_e32 v46, v24
	s_waitcnt lgkmcnt(1)
	v_mov_b32_e32 v47, v28
	v_mov_b32_e32 v20, v17
	v_mov_b32_e32 v28, v25
	v_mov_b32_e32 v16, v18
	v_mov_b32_e32 v17, v22
	v_mov_b32_e32 v24, v26
	v_mov_b32_e32 v25, v30
	v_mov_b32_e32 v22, v19
	v_mov_b32_e32 v30, v27
	v_add_u32_e32 v12, 16, v12
	s_waitcnt vmcnt(39)
	v_pk_fma_f32 v[8:9], v[210:211], v[44:45], v[8:9] op_sel_hi:[0,1,1]
	v_pk_fma_f32 v[10:11], v[210:211], v[46:47], v[10:11] op_sel_hi:[0,1,1]
	s_waitcnt lgkmcnt(0)
	v_fmac_f32_e32 v2, v210, v32
	s_waitcnt vmcnt(38)
	v_pk_fma_f32 v[8:9], v[210:211], v[20:21], v[8:9] op_sel:[1,0,0] op_sel_hi:[1,1,1]
	v_pk_fma_f32 v[10:11], v[210:211], v[28:29], v[10:11] op_sel:[1,0,0] op_sel_hi:[1,1,1]
	v_fmac_f32_e32 v2, v211, v33
	s_waitcnt vmcnt(37)
	v_pk_fma_f32 v[8:9], v[212:213], v[16:17], v[8:9] op_sel_hi:[0,1,1]
	v_pk_fma_f32 v[10:11], v[212:213], v[24:25], v[10:11] op_sel_hi:[0,1,1]
	v_fmac_f32_e32 v2, v212, v34
	s_waitcnt vmcnt(36)
	v_pk_fma_f32 v[8:9], v[212:213], v[22:23], v[8:9] op_sel:[1,0,0] op_sel_hi:[1,1,1]
	v_pk_fma_f32 v[10:11], v[212:213], v[30:31], v[10:11] op_sel:[1,0,0] op_sel_hi:[1,1,1]
	v_fmac_f32_e32 v2, v213, v35
	s_add_u32 s8, s12, 0xf0000
	s_addc_u32 s9, s13, 0
	global_load_dword v210, v6, s[8:9]
	s_add_u32 s10, s12, 0xf3000
	s_addc_u32 s11, s13, 0
	global_load_dword v211, v6, s[10:11]
	s_add_u32 s8, s12, 0xf6000
	s_addc_u32 s9, s13, 0
	global_load_dword v212, v6, s[8:9]
	s_add_u32 s10, s12, 0xf9000
	s_addc_u32 s11, s13, 0
	global_load_dword v213, v6, s[10:11]
	ds_read_b128 v[16:19], v12
	ds_read_b128 v[20:23], v12 offset:4096
	ds_read_b128 v[24:27], v12 offset:8192
	ds_read_b128 v[28:31], v12 offset:12288
	ds_read_b128 v[32:35], v12 offset:16384
	s_waitcnt lgkmcnt(4)
	v_mov_b32_e32 v44, v16
	s_waitcnt lgkmcnt(3)
	v_mov_b32_e32 v45, v20
	s_waitcnt lgkmcnt(2)
	v_mov_b32_e32 v46, v24
	s_waitcnt lgkmcnt(1)
	v_mov_b32_e32 v47, v28
	v_mov_b32_e32 v20, v17
	v_mov_b32_e32 v28, v25
	v_mov_b32_e32 v16, v18
	v_mov_b32_e32 v17, v22
	v_mov_b32_e32 v24, v26
	v_mov_b32_e32 v25, v30
	v_mov_b32_e32 v22, v19
	v_mov_b32_e32 v30, v27
	v_add_u32_e32 v12, 16, v12
	s_waitcnt vmcnt(39)
	v_pk_fma_f32 v[8:9], v[214:215], v[44:45], v[8:9] op_sel_hi:[0,1,1]
	v_pk_fma_f32 v[10:11], v[214:215], v[46:47], v[10:11] op_sel_hi:[0,1,1]
	s_waitcnt lgkmcnt(0)
	v_fmac_f32_e32 v2, v214, v32
	s_waitcnt vmcnt(38)
	v_pk_fma_f32 v[8:9], v[214:215], v[20:21], v[8:9] op_sel:[1,0,0] op_sel_hi:[1,1,1]
	v_pk_fma_f32 v[10:11], v[214:215], v[28:29], v[10:11] op_sel:[1,0,0] op_sel_hi:[1,1,1]
	v_fmac_f32_e32 v2, v215, v33
	s_waitcnt vmcnt(37)
	v_pk_fma_f32 v[8:9], v[216:217], v[16:17], v[8:9] op_sel_hi:[0,1,1]
	v_pk_fma_f32 v[10:11], v[216:217], v[24:25], v[10:11] op_sel_hi:[0,1,1]
	v_fmac_f32_e32 v2, v216, v34
	s_waitcnt vmcnt(36)
	v_pk_fma_f32 v[8:9], v[216:217], v[22:23], v[8:9] op_sel:[1,0,0] op_sel_hi:[1,1,1]
	v_pk_fma_f32 v[10:11], v[216:217], v[30:31], v[10:11] op_sel:[1,0,0] op_sel_hi:[1,1,1]
	v_fmac_f32_e32 v2, v217, v35
	s_add_u32 s8, s12, 0xfc000
	s_addc_u32 s9, s13, 0
	global_load_dword v214, v6, s[8:9]
	s_add_u32 s10, s12, 0xff000
	s_addc_u32 s11, s13, 0
	global_load_dword v215, v6, s[10:11]
	s_add_u32 s8, s12, 0x102000
	s_addc_u32 s9, s13, 0
	global_load_dword v216, v6, s[8:9]
	s_add_u32 s10, s12, 0x105000
	s_addc_u32 s11, s13, 0
	global_load_dword v217, v6, s[10:11]
	ds_read_b128 v[16:19], v12
	ds_read_b128 v[20:23], v12 offset:4096
	ds_read_b128 v[24:27], v12 offset:8192
	ds_read_b128 v[28:31], v12 offset:12288
	ds_read_b128 v[32:35], v12 offset:16384
	s_waitcnt lgkmcnt(4)
	v_mov_b32_e32 v44, v16
	s_waitcnt lgkmcnt(3)
	v_mov_b32_e32 v45, v20
	s_waitcnt lgkmcnt(2)
	v_mov_b32_e32 v46, v24
	s_waitcnt lgkmcnt(1)
	v_mov_b32_e32 v47, v28
	v_mov_b32_e32 v20, v17
	v_mov_b32_e32 v28, v25
	v_mov_b32_e32 v16, v18
	v_mov_b32_e32 v17, v22
	v_mov_b32_e32 v24, v26
	v_mov_b32_e32 v25, v30
	v_mov_b32_e32 v22, v19
	v_mov_b32_e32 v30, v27
	v_add_u32_e32 v12, 16, v12
	s_waitcnt vmcnt(39)
	v_pk_fma_f32 v[8:9], v[218:219], v[44:45], v[8:9] op_sel_hi:[0,1,1]
	v_pk_fma_f32 v[10:11], v[218:219], v[46:47], v[10:11] op_sel_hi:[0,1,1]
	s_waitcnt lgkmcnt(0)
	v_fmac_f32_e32 v2, v218, v32
	s_waitcnt vmcnt(38)
	v_pk_fma_f32 v[8:9], v[218:219], v[20:21], v[8:9] op_sel:[1,0,0] op_sel_hi:[1,1,1]
	v_pk_fma_f32 v[10:11], v[218:219], v[28:29], v[10:11] op_sel:[1,0,0] op_sel_hi:[1,1,1]
	v_fmac_f32_e32 v2, v219, v33
	s_waitcnt vmcnt(37)
	v_pk_fma_f32 v[8:9], v[220:221], v[16:17], v[8:9] op_sel_hi:[0,1,1]
	v_pk_fma_f32 v[10:11], v[220:221], v[24:25], v[10:11] op_sel_hi:[0,1,1]
	v_fmac_f32_e32 v2, v220, v34
	s_waitcnt vmcnt(36)
	v_pk_fma_f32 v[8:9], v[220:221], v[22:23], v[8:9] op_sel:[1,0,0] op_sel_hi:[1,1,1]
	v_pk_fma_f32 v[10:11], v[220:221], v[30:31], v[10:11] op_sel:[1,0,0] op_sel_hi:[1,1,1]
	v_fmac_f32_e32 v2, v221, v35
	s_add_u32 s8, s12, 0x108000
	s_addc_u32 s9, s13, 0
	global_load_dword v218, v6, s[8:9]
	s_add_u32 s10, s12, 0x10b000
	s_addc_u32 s11, s13, 0
	global_load_dword v219, v6, s[10:11]
	s_add_u32 s8, s12, 0x10e000
	s_addc_u32 s9, s13, 0
	global_load_dword v220, v6, s[8:9]
	s_add_u32 s10, s12, 0x111000
	s_addc_u32 s11, s13, 0
	global_load_dword v221, v6, s[10:11]
	ds_read_b128 v[16:19], v12
	ds_read_b128 v[20:23], v12 offset:4096
	ds_read_b128 v[24:27], v12 offset:8192
	ds_read_b128 v[28:31], v12 offset:12288
	ds_read_b128 v[32:35], v12 offset:16384
	s_waitcnt lgkmcnt(4)
	v_mov_b32_e32 v44, v16
	s_waitcnt lgkmcnt(3)
	v_mov_b32_e32 v45, v20
	s_waitcnt lgkmcnt(2)
	v_mov_b32_e32 v46, v24
	s_waitcnt lgkmcnt(1)
	v_mov_b32_e32 v47, v28
	v_mov_b32_e32 v20, v17
	v_mov_b32_e32 v28, v25
	v_mov_b32_e32 v16, v18
	v_mov_b32_e32 v17, v22
	v_mov_b32_e32 v24, v26
	v_mov_b32_e32 v25, v30
	v_mov_b32_e32 v22, v19
	v_mov_b32_e32 v30, v27
	v_add_u32_e32 v12, 16, v12
	s_waitcnt vmcnt(39)
	v_pk_fma_f32 v[8:9], v[222:223], v[44:45], v[8:9] op_sel_hi:[0,1,1]
	v_pk_fma_f32 v[10:11], v[222:223], v[46:47], v[10:11] op_sel_hi:[0,1,1]
	s_waitcnt lgkmcnt(0)
	v_fmac_f32_e32 v2, v222, v32
	s_waitcnt vmcnt(38)
	v_pk_fma_f32 v[8:9], v[222:223], v[20:21], v[8:9] op_sel:[1,0,0] op_sel_hi:[1,1,1]
	v_pk_fma_f32 v[10:11], v[222:223], v[28:29], v[10:11] op_sel:[1,0,0] op_sel_hi:[1,1,1]
	v_fmac_f32_e32 v2, v223, v33
	s_waitcnt vmcnt(37)
	v_pk_fma_f32 v[8:9], v[224:225], v[16:17], v[8:9] op_sel_hi:[0,1,1]
	v_pk_fma_f32 v[10:11], v[224:225], v[24:25], v[10:11] op_sel_hi:[0,1,1]
	v_fmac_f32_e32 v2, v224, v34
	s_waitcnt vmcnt(36)
	v_pk_fma_f32 v[8:9], v[224:225], v[22:23], v[8:9] op_sel:[1,0,0] op_sel_hi:[1,1,1]
	v_pk_fma_f32 v[10:11], v[224:225], v[30:31], v[10:11] op_sel:[1,0,0] op_sel_hi:[1,1,1]
	v_fmac_f32_e32 v2, v225, v35
	s_add_u32 s8, s12, 0x114000
	s_addc_u32 s9, s13, 0
	global_load_dword v222, v6, s[8:9]
	s_add_u32 s10, s12, 0x117000
	s_addc_u32 s11, s13, 0
	global_load_dword v223, v6, s[10:11]
	s_add_u32 s8, s12, 0x11a000
	s_addc_u32 s9, s13, 0
	global_load_dword v224, v6, s[8:9]
	s_add_u32 s10, s12, 0x11d000
	s_addc_u32 s11, s13, 0
	global_load_dword v225, v6, s[10:11]
	ds_read_b128 v[16:19], v12
	ds_read_b128 v[20:23], v12 offset:4096
	ds_read_b128 v[24:27], v12 offset:8192
	ds_read_b128 v[28:31], v12 offset:12288
	ds_read_b128 v[32:35], v12 offset:16384
	s_waitcnt lgkmcnt(4)
	v_mov_b32_e32 v44, v16
	s_waitcnt lgkmcnt(3)
	v_mov_b32_e32 v45, v20
	s_waitcnt lgkmcnt(2)
	v_mov_b32_e32 v46, v24
	s_waitcnt lgkmcnt(1)
	v_mov_b32_e32 v47, v28
	v_mov_b32_e32 v20, v17
	v_mov_b32_e32 v28, v25
	v_mov_b32_e32 v16, v18
	v_mov_b32_e32 v17, v22
	v_mov_b32_e32 v24, v26
	v_mov_b32_e32 v25, v30
	v_mov_b32_e32 v22, v19
	v_mov_b32_e32 v30, v27
	v_add_u32_e32 v12, 16, v12
	s_waitcnt vmcnt(39)
	v_pk_fma_f32 v[8:9], v[226:227], v[44:45], v[8:9] op_sel_hi:[0,1,1]
	v_pk_fma_f32 v[10:11], v[226:227], v[46:47], v[10:11] op_sel_hi:[0,1,1]
	s_waitcnt lgkmcnt(0)
	v_fmac_f32_e32 v2, v226, v32
	s_waitcnt vmcnt(38)
	v_pk_fma_f32 v[8:9], v[226:227], v[20:21], v[8:9] op_sel:[1,0,0] op_sel_hi:[1,1,1]
	v_pk_fma_f32 v[10:11], v[226:227], v[28:29], v[10:11] op_sel:[1,0,0] op_sel_hi:[1,1,1]
	v_fmac_f32_e32 v2, v227, v33
	s_waitcnt vmcnt(37)
	v_pk_fma_f32 v[8:9], v[228:229], v[16:17], v[8:9] op_sel_hi:[0,1,1]
	v_pk_fma_f32 v[10:11], v[228:229], v[24:25], v[10:11] op_sel_hi:[0,1,1]
	v_fmac_f32_e32 v2, v228, v34
	s_waitcnt vmcnt(36)
	v_pk_fma_f32 v[8:9], v[228:229], v[22:23], v[8:9] op_sel:[1,0,0] op_sel_hi:[1,1,1]
	v_pk_fma_f32 v[10:11], v[228:229], v[30:31], v[10:11] op_sel:[1,0,0] op_sel_hi:[1,1,1]
	v_fmac_f32_e32 v2, v229, v35
	s_add_u32 s8, s12, 0x120000
	s_addc_u32 s9, s13, 0
	global_load_dword v226, v6, s[8:9]
	s_add_u32 s10, s12, 0x123000
	s_addc_u32 s11, s13, 0
	global_load_dword v227, v6, s[10:11]
	s_add_u32 s8, s12, 0x126000
	s_addc_u32 s9, s13, 0
	global_load_dword v228, v6, s[8:9]
	s_add_u32 s10, s12, 0x129000
	s_addc_u32 s11, s13, 0
	global_load_dword v229, v6, s[10:11]
	ds_read_b128 v[16:19], v12
	ds_read_b128 v[20:23], v12 offset:4096
	ds_read_b128 v[24:27], v12 offset:8192
	ds_read_b128 v[28:31], v12 offset:12288
	ds_read_b128 v[32:35], v12 offset:16384
	s_waitcnt lgkmcnt(4)
	v_mov_b32_e32 v44, v16
	s_waitcnt lgkmcnt(3)
	v_mov_b32_e32 v45, v20
	s_waitcnt lgkmcnt(2)
	v_mov_b32_e32 v46, v24
	s_waitcnt lgkmcnt(1)
	v_mov_b32_e32 v47, v28
	v_mov_b32_e32 v20, v17
	v_mov_b32_e32 v28, v25
	v_mov_b32_e32 v16, v18
	v_mov_b32_e32 v17, v22
	v_mov_b32_e32 v24, v26
	v_mov_b32_e32 v25, v30
	v_mov_b32_e32 v22, v19
	v_mov_b32_e32 v30, v27
	v_add_u32_e32 v12, 16, v12
	s_waitcnt vmcnt(39)
	v_pk_fma_f32 v[8:9], v[230:231], v[44:45], v[8:9] op_sel_hi:[0,1,1]
	v_pk_fma_f32 v[10:11], v[230:231], v[46:47], v[10:11] op_sel_hi:[0,1,1]
	s_waitcnt lgkmcnt(0)
	v_fmac_f32_e32 v2, v230, v32
	s_waitcnt vmcnt(38)
	v_pk_fma_f32 v[8:9], v[230:231], v[20:21], v[8:9] op_sel:[1,0,0] op_sel_hi:[1,1,1]
	v_pk_fma_f32 v[10:11], v[230:231], v[28:29], v[10:11] op_sel:[1,0,0] op_sel_hi:[1,1,1]
	v_fmac_f32_e32 v2, v231, v33
	s_waitcnt vmcnt(37)
	v_pk_fma_f32 v[8:9], v[232:233], v[16:17], v[8:9] op_sel_hi:[0,1,1]
	v_pk_fma_f32 v[10:11], v[232:233], v[24:25], v[10:11] op_sel_hi:[0,1,1]
	v_fmac_f32_e32 v2, v232, v34
	s_waitcnt vmcnt(36)
	v_pk_fma_f32 v[8:9], v[232:233], v[22:23], v[8:9] op_sel:[1,0,0] op_sel_hi:[1,1,1]
	v_pk_fma_f32 v[10:11], v[232:233], v[30:31], v[10:11] op_sel:[1,0,0] op_sel_hi:[1,1,1]
	v_fmac_f32_e32 v2, v233, v35
	s_add_u32 s8, s12, 0x12c000
	s_addc_u32 s9, s13, 0
	global_load_dword v230, v6, s[8:9]
	s_add_u32 s10, s12, 0x12f000
	s_addc_u32 s11, s13, 0
	global_load_dword v231, v6, s[10:11]
	s_add_u32 s8, s12, 0x132000
	s_addc_u32 s9, s13, 0
	global_load_dword v232, v6, s[8:9]
	s_add_u32 s10, s12, 0x135000
	s_addc_u32 s11, s13, 0
	global_load_dword v233, v6, s[10:11]
	ds_read_b128 v[16:19], v12
	ds_read_b128 v[20:23], v12 offset:4096
	ds_read_b128 v[24:27], v12 offset:8192
	ds_read_b128 v[28:31], v12 offset:12288
	ds_read_b128 v[32:35], v12 offset:16384
	s_waitcnt lgkmcnt(4)
	v_mov_b32_e32 v44, v16
	s_waitcnt lgkmcnt(3)
	v_mov_b32_e32 v45, v20
	s_waitcnt lgkmcnt(2)
	v_mov_b32_e32 v46, v24
	s_waitcnt lgkmcnt(1)
	v_mov_b32_e32 v47, v28
	v_mov_b32_e32 v20, v17
	v_mov_b32_e32 v28, v25
	v_mov_b32_e32 v16, v18
	v_mov_b32_e32 v17, v22
	v_mov_b32_e32 v24, v26
	v_mov_b32_e32 v25, v30
	v_mov_b32_e32 v22, v19
	v_mov_b32_e32 v30, v27
	v_add_u32_e32 v12, 16, v12
	s_waitcnt vmcnt(39)
	v_pk_fma_f32 v[8:9], v[234:235], v[44:45], v[8:9] op_sel_hi:[0,1,1]
	v_pk_fma_f32 v[10:11], v[234:235], v[46:47], v[10:11] op_sel_hi:[0,1,1]
	s_waitcnt lgkmcnt(0)
	v_fmac_f32_e32 v2, v234, v32
	s_waitcnt vmcnt(38)
	v_pk_fma_f32 v[8:9], v[234:235], v[20:21], v[8:9] op_sel:[1,0,0] op_sel_hi:[1,1,1]
	v_pk_fma_f32 v[10:11], v[234:235], v[28:29], v[10:11] op_sel:[1,0,0] op_sel_hi:[1,1,1]
	v_fmac_f32_e32 v2, v235, v33
	s_waitcnt vmcnt(37)
	v_pk_fma_f32 v[8:9], v[236:237], v[16:17], v[8:9] op_sel_hi:[0,1,1]
	v_pk_fma_f32 v[10:11], v[236:237], v[24:25], v[10:11] op_sel_hi:[0,1,1]
	v_fmac_f32_e32 v2, v236, v34
	s_waitcnt vmcnt(36)
	v_pk_fma_f32 v[8:9], v[236:237], v[22:23], v[8:9] op_sel:[1,0,0] op_sel_hi:[1,1,1]
	v_pk_fma_f32 v[10:11], v[236:237], v[30:31], v[10:11] op_sel:[1,0,0] op_sel_hi:[1,1,1]
	v_fmac_f32_e32 v2, v237, v35
	s_add_u32 s8, s12, 0x138000
	s_addc_u32 s9, s13, 0
	global_load_dword v234, v6, s[8:9]
	s_add_u32 s10, s12, 0x13b000
	s_addc_u32 s11, s13, 0
	global_load_dword v235, v6, s[10:11]
	s_add_u32 s8, s12, 0x13e000
	s_addc_u32 s9, s13, 0
	global_load_dword v236, v6, s[8:9]
	s_add_u32 s10, s12, 0x141000
	s_addc_u32 s11, s13, 0
	global_load_dword v237, v6, s[10:11]
	ds_read_b128 v[16:19], v12
	ds_read_b128 v[20:23], v12 offset:4096
	ds_read_b128 v[24:27], v12 offset:8192
	ds_read_b128 v[28:31], v12 offset:12288
	ds_read_b128 v[32:35], v12 offset:16384
	s_waitcnt lgkmcnt(4)
	v_mov_b32_e32 v44, v16
	s_waitcnt lgkmcnt(3)
	v_mov_b32_e32 v45, v20
	s_waitcnt lgkmcnt(2)
	v_mov_b32_e32 v46, v24
	s_waitcnt lgkmcnt(1)
	v_mov_b32_e32 v47, v28
	v_mov_b32_e32 v20, v17
	v_mov_b32_e32 v28, v25
	v_mov_b32_e32 v16, v18
	v_mov_b32_e32 v17, v22
	v_mov_b32_e32 v24, v26
	v_mov_b32_e32 v25, v30
	v_mov_b32_e32 v22, v19
	v_mov_b32_e32 v30, v27
	v_add_u32_e32 v12, 16, v12
	s_waitcnt vmcnt(39)
	v_pk_fma_f32 v[8:9], v[238:239], v[44:45], v[8:9] op_sel_hi:[0,1,1]
	v_pk_fma_f32 v[10:11], v[238:239], v[46:47], v[10:11] op_sel_hi:[0,1,1]
	s_waitcnt lgkmcnt(0)
	v_fmac_f32_e32 v2, v238, v32
	s_waitcnt vmcnt(38)
	v_pk_fma_f32 v[8:9], v[238:239], v[20:21], v[8:9] op_sel:[1,0,0] op_sel_hi:[1,1,1]
	v_pk_fma_f32 v[10:11], v[238:239], v[28:29], v[10:11] op_sel:[1,0,0] op_sel_hi:[1,1,1]
	v_fmac_f32_e32 v2, v239, v33
	s_waitcnt vmcnt(37)
	v_pk_fma_f32 v[8:9], v[240:241], v[16:17], v[8:9] op_sel_hi:[0,1,1]
	v_pk_fma_f32 v[10:11], v[240:241], v[24:25], v[10:11] op_sel_hi:[0,1,1]
	v_fmac_f32_e32 v2, v240, v34
	s_waitcnt vmcnt(36)
	v_pk_fma_f32 v[8:9], v[240:241], v[22:23], v[8:9] op_sel:[1,0,0] op_sel_hi:[1,1,1]
	v_pk_fma_f32 v[10:11], v[240:241], v[30:31], v[10:11] op_sel:[1,0,0] op_sel_hi:[1,1,1]
	v_fmac_f32_e32 v2, v241, v35
	s_add_u32 s8, s12, 0x144000
	s_addc_u32 s9, s13, 0
	global_load_dword v238, v6, s[8:9]
	s_add_u32 s10, s12, 0x147000
	s_addc_u32 s11, s13, 0
	global_load_dword v239, v6, s[10:11]
	s_add_u32 s8, s12, 0x14a000
	s_addc_u32 s9, s13, 0
	global_load_dword v240, v6, s[8:9]
	s_add_u32 s10, s12, 0x14d000
	s_addc_u32 s11, s13, 0
	global_load_dword v241, v6, s[10:11]
	ds_read_b128 v[16:19], v12
	ds_read_b128 v[20:23], v12 offset:4096
	ds_read_b128 v[24:27], v12 offset:8192
	ds_read_b128 v[28:31], v12 offset:12288
	ds_read_b128 v[32:35], v12 offset:16384
	s_waitcnt lgkmcnt(4)
	v_mov_b32_e32 v44, v16
	s_waitcnt lgkmcnt(3)
	v_mov_b32_e32 v45, v20
	s_waitcnt lgkmcnt(2)
	v_mov_b32_e32 v46, v24
	s_waitcnt lgkmcnt(1)
	v_mov_b32_e32 v47, v28
	v_mov_b32_e32 v20, v17
	v_mov_b32_e32 v28, v25
	v_mov_b32_e32 v16, v18
	v_mov_b32_e32 v17, v22
	v_mov_b32_e32 v24, v26
	v_mov_b32_e32 v25, v30
	v_mov_b32_e32 v22, v19
	v_mov_b32_e32 v30, v27
	v_add_u32_e32 v12, 16, v12
	s_waitcnt vmcnt(39)
	v_pk_fma_f32 v[8:9], v[242:243], v[44:45], v[8:9] op_sel_hi:[0,1,1]
	v_pk_fma_f32 v[10:11], v[242:243], v[46:47], v[10:11] op_sel_hi:[0,1,1]
	s_waitcnt lgkmcnt(0)
	v_fmac_f32_e32 v2, v242, v32
	s_waitcnt vmcnt(38)
	v_pk_fma_f32 v[8:9], v[242:243], v[20:21], v[8:9] op_sel:[1,0,0] op_sel_hi:[1,1,1]
	v_pk_fma_f32 v[10:11], v[242:243], v[28:29], v[10:11] op_sel:[1,0,0] op_sel_hi:[1,1,1]
	v_fmac_f32_e32 v2, v243, v33
	s_waitcnt vmcnt(37)
	v_pk_fma_f32 v[8:9], v[244:245], v[16:17], v[8:9] op_sel_hi:[0,1,1]
	v_pk_fma_f32 v[10:11], v[244:245], v[24:25], v[10:11] op_sel_hi:[0,1,1]
	v_fmac_f32_e32 v2, v244, v34
	s_waitcnt vmcnt(36)
	v_pk_fma_f32 v[8:9], v[244:245], v[22:23], v[8:9] op_sel:[1,0,0] op_sel_hi:[1,1,1]
	v_pk_fma_f32 v[10:11], v[244:245], v[30:31], v[10:11] op_sel:[1,0,0] op_sel_hi:[1,1,1]
	v_fmac_f32_e32 v2, v245, v35
	s_add_u32 s8, s12, 0x150000
	s_addc_u32 s9, s13, 0
	global_load_dword v242, v6, s[8:9]
	s_add_u32 s10, s12, 0x153000
	s_addc_u32 s11, s13, 0
	global_load_dword v243, v6, s[10:11]
	s_add_u32 s8, s12, 0x156000
	s_addc_u32 s9, s13, 0
	global_load_dword v244, v6, s[8:9]
	s_add_u32 s10, s12, 0x159000
	s_addc_u32 s11, s13, 0
	global_load_dword v245, v6, s[10:11]
	ds_read_b128 v[16:19], v12
	ds_read_b128 v[20:23], v12 offset:4096
	ds_read_b128 v[24:27], v12 offset:8192
	ds_read_b128 v[28:31], v12 offset:12288
	ds_read_b128 v[32:35], v12 offset:16384
	s_waitcnt lgkmcnt(4)
	v_mov_b32_e32 v44, v16
	s_waitcnt lgkmcnt(3)
	v_mov_b32_e32 v45, v20
	s_waitcnt lgkmcnt(2)
	v_mov_b32_e32 v46, v24
	s_waitcnt lgkmcnt(1)
	v_mov_b32_e32 v47, v28
	v_mov_b32_e32 v20, v17
	v_mov_b32_e32 v28, v25
	v_mov_b32_e32 v16, v18
	v_mov_b32_e32 v17, v22
	v_mov_b32_e32 v24, v26
	v_mov_b32_e32 v25, v30
	v_mov_b32_e32 v22, v19
	v_mov_b32_e32 v30, v27
	v_add_u32_e32 v12, 16, v12
	s_waitcnt vmcnt(39)
	v_pk_fma_f32 v[8:9], v[246:247], v[44:45], v[8:9] op_sel_hi:[0,1,1]
	v_pk_fma_f32 v[10:11], v[246:247], v[46:47], v[10:11] op_sel_hi:[0,1,1]
	s_waitcnt lgkmcnt(0)
	v_fmac_f32_e32 v2, v246, v32
	s_waitcnt vmcnt(38)
	v_pk_fma_f32 v[8:9], v[246:247], v[20:21], v[8:9] op_sel:[1,0,0] op_sel_hi:[1,1,1]
	v_pk_fma_f32 v[10:11], v[246:247], v[28:29], v[10:11] op_sel:[1,0,0] op_sel_hi:[1,1,1]
	v_fmac_f32_e32 v2, v247, v33
	s_waitcnt vmcnt(37)
	v_pk_fma_f32 v[8:9], v[248:249], v[16:17], v[8:9] op_sel_hi:[0,1,1]
	v_pk_fma_f32 v[10:11], v[248:249], v[24:25], v[10:11] op_sel_hi:[0,1,1]
	v_fmac_f32_e32 v2, v248, v34
	s_waitcnt vmcnt(36)
	v_pk_fma_f32 v[8:9], v[248:249], v[22:23], v[8:9] op_sel:[1,0,0] op_sel_hi:[1,1,1]
	v_pk_fma_f32 v[10:11], v[248:249], v[30:31], v[10:11] op_sel:[1,0,0] op_sel_hi:[1,1,1]
	v_fmac_f32_e32 v2, v249, v35
	s_add_u32 s8, s12, 0x15c000
	s_addc_u32 s9, s13, 0
	global_load_dword v246, v6, s[8:9]
	s_add_u32 s10, s12, 0x15f000
	s_addc_u32 s11, s13, 0
	global_load_dword v247, v6, s[10:11]
	s_add_u32 s8, s12, 0x162000
	s_addc_u32 s9, s13, 0
	global_load_dword v248, v6, s[8:9]
	s_add_u32 s10, s12, 0x165000
	s_addc_u32 s11, s13, 0
	global_load_dword v249, v6, s[10:11]
	ds_read_b128 v[16:19], v12
	ds_read_b128 v[20:23], v12 offset:4096
	ds_read_b128 v[24:27], v12 offset:8192
	ds_read_b128 v[28:31], v12 offset:12288
	ds_read_b128 v[32:35], v12 offset:16384
	s_waitcnt lgkmcnt(4)
	v_mov_b32_e32 v44, v16
	s_waitcnt lgkmcnt(3)
	v_mov_b32_e32 v45, v20
	s_waitcnt lgkmcnt(2)
	v_mov_b32_e32 v46, v24
	s_waitcnt lgkmcnt(1)
	v_mov_b32_e32 v47, v28
	v_mov_b32_e32 v20, v17
	v_mov_b32_e32 v28, v25
	v_mov_b32_e32 v16, v18
	v_mov_b32_e32 v17, v22
	v_mov_b32_e32 v24, v26
	v_mov_b32_e32 v25, v30
	v_mov_b32_e32 v22, v19
	v_mov_b32_e32 v30, v27
	v_add_u32_e32 v12, 16, v12
	s_waitcnt vmcnt(39)
	v_pk_fma_f32 v[8:9], v[210:211], v[44:45], v[8:9] op_sel_hi:[0,1,1]
	v_pk_fma_f32 v[10:11], v[210:211], v[46:47], v[10:11] op_sel_hi:[0,1,1]
	s_waitcnt lgkmcnt(0)
	v_fmac_f32_e32 v2, v210, v32
	s_waitcnt vmcnt(38)
	v_pk_fma_f32 v[8:9], v[210:211], v[20:21], v[8:9] op_sel:[1,0,0] op_sel_hi:[1,1,1]
	v_pk_fma_f32 v[10:11], v[210:211], v[28:29], v[10:11] op_sel:[1,0,0] op_sel_hi:[1,1,1]
	v_fmac_f32_e32 v2, v211, v33
	s_waitcnt vmcnt(37)
	v_pk_fma_f32 v[8:9], v[212:213], v[16:17], v[8:9] op_sel_hi:[0,1,1]
	v_pk_fma_f32 v[10:11], v[212:213], v[24:25], v[10:11] op_sel_hi:[0,1,1]
	v_fmac_f32_e32 v2, v212, v34
	s_waitcnt vmcnt(36)
	v_pk_fma_f32 v[8:9], v[212:213], v[22:23], v[8:9] op_sel:[1,0,0] op_sel_hi:[1,1,1]
	v_pk_fma_f32 v[10:11], v[212:213], v[30:31], v[10:11] op_sel:[1,0,0] op_sel_hi:[1,1,1]
	v_fmac_f32_e32 v2, v213, v35
	s_add_u32 s8, s12, 0x168000
	s_addc_u32 s9, s13, 0
	global_load_dword v210, v6, s[8:9]
	s_add_u32 s10, s12, 0x16b000
	s_addc_u32 s11, s13, 0
	global_load_dword v211, v6, s[10:11]
	s_add_u32 s8, s12, 0x16e000
	s_addc_u32 s9, s13, 0
	global_load_dword v212, v6, s[8:9]
	s_add_u32 s10, s12, 0x171000
	s_addc_u32 s11, s13, 0
	global_load_dword v213, v6, s[10:11]
	ds_read_b128 v[16:19], v12
	ds_read_b128 v[20:23], v12 offset:4096
	ds_read_b128 v[24:27], v12 offset:8192
	ds_read_b128 v[28:31], v12 offset:12288
	ds_read_b128 v[32:35], v12 offset:16384
	s_waitcnt lgkmcnt(4)
	v_mov_b32_e32 v44, v16
	s_waitcnt lgkmcnt(3)
	v_mov_b32_e32 v45, v20
	s_waitcnt lgkmcnt(2)
	v_mov_b32_e32 v46, v24
	s_waitcnt lgkmcnt(1)
	v_mov_b32_e32 v47, v28
	v_mov_b32_e32 v20, v17
	v_mov_b32_e32 v28, v25
	v_mov_b32_e32 v16, v18
	v_mov_b32_e32 v17, v22
	v_mov_b32_e32 v24, v26
	v_mov_b32_e32 v25, v30
	v_mov_b32_e32 v22, v19
	v_mov_b32_e32 v30, v27
	v_add_u32_e32 v12, 16, v12
	s_waitcnt vmcnt(39)
	v_pk_fma_f32 v[8:9], v[214:215], v[44:45], v[8:9] op_sel_hi:[0,1,1]
	v_pk_fma_f32 v[10:11], v[214:215], v[46:47], v[10:11] op_sel_hi:[0,1,1]
	s_waitcnt lgkmcnt(0)
	v_fmac_f32_e32 v2, v214, v32
	s_waitcnt vmcnt(38)
	v_pk_fma_f32 v[8:9], v[214:215], v[20:21], v[8:9] op_sel:[1,0,0] op_sel_hi:[1,1,1]
	v_pk_fma_f32 v[10:11], v[214:215], v[28:29], v[10:11] op_sel:[1,0,0] op_sel_hi:[1,1,1]
	v_fmac_f32_e32 v2, v215, v33
	s_waitcnt vmcnt(37)
	v_pk_fma_f32 v[8:9], v[216:217], v[16:17], v[8:9] op_sel_hi:[0,1,1]
	v_pk_fma_f32 v[10:11], v[216:217], v[24:25], v[10:11] op_sel_hi:[0,1,1]
	v_fmac_f32_e32 v2, v216, v34
	s_waitcnt vmcnt(36)
	v_pk_fma_f32 v[8:9], v[216:217], v[22:23], v[8:9] op_sel:[1,0,0] op_sel_hi:[1,1,1]
	v_pk_fma_f32 v[10:11], v[216:217], v[30:31], v[10:11] op_sel:[1,0,0] op_sel_hi:[1,1,1]
	v_fmac_f32_e32 v2, v217, v35
	s_add_u32 s8, s12, 0x174000
	s_addc_u32 s9, s13, 0
	global_load_dword v214, v6, s[8:9]
	s_add_u32 s10, s12, 0x177000
	s_addc_u32 s11, s13, 0
	global_load_dword v215, v6, s[10:11]
	s_add_u32 s8, s12, 0x17a000
	s_addc_u32 s9, s13, 0
	global_load_dword v216, v6, s[8:9]
	s_add_u32 s10, s12, 0x17d000
	s_addc_u32 s11, s13, 0
	global_load_dword v217, v6, s[10:11]
	ds_read_b128 v[16:19], v12
	ds_read_b128 v[20:23], v12 offset:4096
	ds_read_b128 v[24:27], v12 offset:8192
	ds_read_b128 v[28:31], v12 offset:12288
	ds_read_b128 v[32:35], v12 offset:16384
	s_waitcnt lgkmcnt(4)
	v_mov_b32_e32 v44, v16
	s_waitcnt lgkmcnt(3)
	v_mov_b32_e32 v45, v20
	s_waitcnt lgkmcnt(2)
	v_mov_b32_e32 v46, v24
	s_waitcnt lgkmcnt(1)
	v_mov_b32_e32 v47, v28
	v_mov_b32_e32 v20, v17
	v_mov_b32_e32 v28, v25
	v_mov_b32_e32 v16, v18
	v_mov_b32_e32 v17, v22
	v_mov_b32_e32 v24, v26
	v_mov_b32_e32 v25, v30
	v_mov_b32_e32 v22, v19
	v_mov_b32_e32 v30, v27
	v_add_u32_e32 v12, 16, v12
	s_waitcnt vmcnt(39)
	v_pk_fma_f32 v[8:9], v[218:219], v[44:45], v[8:9] op_sel_hi:[0,1,1]
	v_pk_fma_f32 v[10:11], v[218:219], v[46:47], v[10:11] op_sel_hi:[0,1,1]
	s_waitcnt lgkmcnt(0)
	v_fmac_f32_e32 v2, v218, v32
	s_waitcnt vmcnt(38)
	v_pk_fma_f32 v[8:9], v[218:219], v[20:21], v[8:9] op_sel:[1,0,0] op_sel_hi:[1,1,1]
	v_pk_fma_f32 v[10:11], v[218:219], v[28:29], v[10:11] op_sel:[1,0,0] op_sel_hi:[1,1,1]
	v_fmac_f32_e32 v2, v219, v33
	s_waitcnt vmcnt(37)
	v_pk_fma_f32 v[8:9], v[220:221], v[16:17], v[8:9] op_sel_hi:[0,1,1]
	v_pk_fma_f32 v[10:11], v[220:221], v[24:25], v[10:11] op_sel_hi:[0,1,1]
	v_fmac_f32_e32 v2, v220, v34
	s_waitcnt vmcnt(36)
	v_pk_fma_f32 v[8:9], v[220:221], v[22:23], v[8:9] op_sel:[1,0,0] op_sel_hi:[1,1,1]
	v_pk_fma_f32 v[10:11], v[220:221], v[30:31], v[10:11] op_sel:[1,0,0] op_sel_hi:[1,1,1]
	v_fmac_f32_e32 v2, v221, v35
	ds_read_b128 v[16:19], v12
	ds_read_b128 v[20:23], v12 offset:4096
	ds_read_b128 v[24:27], v12 offset:8192
	ds_read_b128 v[28:31], v12 offset:12288
	ds_read_b128 v[32:35], v12 offset:16384
	s_waitcnt lgkmcnt(4)
	v_mov_b32_e32 v44, v16
	s_waitcnt lgkmcnt(3)
	v_mov_b32_e32 v45, v20
	s_waitcnt lgkmcnt(2)
	v_mov_b32_e32 v46, v24
	s_waitcnt lgkmcnt(1)
	v_mov_b32_e32 v47, v28
	v_mov_b32_e32 v20, v17
	v_mov_b32_e32 v28, v25
	v_mov_b32_e32 v16, v18
	v_mov_b32_e32 v17, v22
	v_mov_b32_e32 v24, v26
	v_mov_b32_e32 v25, v30
	v_mov_b32_e32 v22, v19
	v_mov_b32_e32 v30, v27
	v_add_u32_e32 v12, 16, v12
	s_waitcnt vmcnt(35)
	v_pk_fma_f32 v[8:9], v[222:223], v[44:45], v[8:9] op_sel_hi:[0,1,1]
	v_pk_fma_f32 v[10:11], v[222:223], v[46:47], v[10:11] op_sel_hi:[0,1,1]
	s_waitcnt lgkmcnt(0)
	v_fmac_f32_e32 v2, v222, v32
	s_waitcnt vmcnt(34)
	v_pk_fma_f32 v[8:9], v[222:223], v[20:21], v[8:9] op_sel:[1,0,0] op_sel_hi:[1,1,1]
	v_pk_fma_f32 v[10:11], v[222:223], v[28:29], v[10:11] op_sel:[1,0,0] op_sel_hi:[1,1,1]
	v_fmac_f32_e32 v2, v223, v33
	s_waitcnt vmcnt(33)
	v_pk_fma_f32 v[8:9], v[224:225], v[16:17], v[8:9] op_sel_hi:[0,1,1]
	v_pk_fma_f32 v[10:11], v[224:225], v[24:25], v[10:11] op_sel_hi:[0,1,1]
	v_fmac_f32_e32 v2, v224, v34
	s_waitcnt vmcnt(32)
	v_pk_fma_f32 v[8:9], v[224:225], v[22:23], v[8:9] op_sel:[1,0,0] op_sel_hi:[1,1,1]
	v_pk_fma_f32 v[10:11], v[224:225], v[30:31], v[10:11] op_sel:[1,0,0] op_sel_hi:[1,1,1]
	v_fmac_f32_e32 v2, v225, v35
	ds_read_b128 v[16:19], v12
	ds_read_b128 v[20:23], v12 offset:4096
	ds_read_b128 v[24:27], v12 offset:8192
	ds_read_b128 v[28:31], v12 offset:12288
	ds_read_b128 v[32:35], v12 offset:16384
	s_waitcnt lgkmcnt(4)
	v_mov_b32_e32 v44, v16
	s_waitcnt lgkmcnt(3)
	v_mov_b32_e32 v45, v20
	s_waitcnt lgkmcnt(2)
	v_mov_b32_e32 v46, v24
	s_waitcnt lgkmcnt(1)
	v_mov_b32_e32 v47, v28
	v_mov_b32_e32 v20, v17
	v_mov_b32_e32 v28, v25
	v_mov_b32_e32 v16, v18
	v_mov_b32_e32 v17, v22
	v_mov_b32_e32 v24, v26
	v_mov_b32_e32 v25, v30
	v_mov_b32_e32 v22, v19
	v_mov_b32_e32 v30, v27
	v_add_u32_e32 v12, 16, v12
	s_waitcnt vmcnt(31)
	v_pk_fma_f32 v[8:9], v[226:227], v[44:45], v[8:9] op_sel_hi:[0,1,1]
	v_pk_fma_f32 v[10:11], v[226:227], v[46:47], v[10:11] op_sel_hi:[0,1,1]
	s_waitcnt lgkmcnt(0)
	v_fmac_f32_e32 v2, v226, v32
	s_waitcnt vmcnt(30)
	v_pk_fma_f32 v[8:9], v[226:227], v[20:21], v[8:9] op_sel:[1,0,0] op_sel_hi:[1,1,1]
	v_pk_fma_f32 v[10:11], v[226:227], v[28:29], v[10:11] op_sel:[1,0,0] op_sel_hi:[1,1,1]
	v_fmac_f32_e32 v2, v227, v33
	s_waitcnt vmcnt(29)
	v_pk_fma_f32 v[8:9], v[228:229], v[16:17], v[8:9] op_sel_hi:[0,1,1]
	v_pk_fma_f32 v[10:11], v[228:229], v[24:25], v[10:11] op_sel_hi:[0,1,1]
	v_fmac_f32_e32 v2, v228, v34
	s_waitcnt vmcnt(28)
	v_pk_fma_f32 v[8:9], v[228:229], v[22:23], v[8:9] op_sel:[1,0,0] op_sel_hi:[1,1,1]
	v_pk_fma_f32 v[10:11], v[228:229], v[30:31], v[10:11] op_sel:[1,0,0] op_sel_hi:[1,1,1]
	v_fmac_f32_e32 v2, v229, v35
	ds_read_b128 v[16:19], v12
	ds_read_b128 v[20:23], v12 offset:4096
	ds_read_b128 v[24:27], v12 offset:8192
	ds_read_b128 v[28:31], v12 offset:12288
	ds_read_b128 v[32:35], v12 offset:16384
	s_waitcnt lgkmcnt(4)
	v_mov_b32_e32 v44, v16
	s_waitcnt lgkmcnt(3)
	v_mov_b32_e32 v45, v20
	s_waitcnt lgkmcnt(2)
	v_mov_b32_e32 v46, v24
	s_waitcnt lgkmcnt(1)
	v_mov_b32_e32 v47, v28
	v_mov_b32_e32 v20, v17
	v_mov_b32_e32 v28, v25
	v_mov_b32_e32 v16, v18
	v_mov_b32_e32 v17, v22
	v_mov_b32_e32 v24, v26
	v_mov_b32_e32 v25, v30
	v_mov_b32_e32 v22, v19
	v_mov_b32_e32 v30, v27
	v_add_u32_e32 v12, 16, v12
	s_waitcnt vmcnt(27)
	v_pk_fma_f32 v[8:9], v[230:231], v[44:45], v[8:9] op_sel_hi:[0,1,1]
	v_pk_fma_f32 v[10:11], v[230:231], v[46:47], v[10:11] op_sel_hi:[0,1,1]
	s_waitcnt lgkmcnt(0)
	v_fmac_f32_e32 v2, v230, v32
	s_waitcnt vmcnt(26)
	v_pk_fma_f32 v[8:9], v[230:231], v[20:21], v[8:9] op_sel:[1,0,0] op_sel_hi:[1,1,1]
	v_pk_fma_f32 v[10:11], v[230:231], v[28:29], v[10:11] op_sel:[1,0,0] op_sel_hi:[1,1,1]
	v_fmac_f32_e32 v2, v231, v33
	s_waitcnt vmcnt(25)
	v_pk_fma_f32 v[8:9], v[232:233], v[16:17], v[8:9] op_sel_hi:[0,1,1]
	v_pk_fma_f32 v[10:11], v[232:233], v[24:25], v[10:11] op_sel_hi:[0,1,1]
	v_fmac_f32_e32 v2, v232, v34
	s_waitcnt vmcnt(24)
	v_pk_fma_f32 v[8:9], v[232:233], v[22:23], v[8:9] op_sel:[1,0,0] op_sel_hi:[1,1,1]
	v_pk_fma_f32 v[10:11], v[232:233], v[30:31], v[10:11] op_sel:[1,0,0] op_sel_hi:[1,1,1]
	v_fmac_f32_e32 v2, v233, v35
	ds_read_b128 v[16:19], v12
	ds_read_b128 v[20:23], v12 offset:4096
	ds_read_b128 v[24:27], v12 offset:8192
	ds_read_b128 v[28:31], v12 offset:12288
	ds_read_b128 v[32:35], v12 offset:16384
	s_waitcnt lgkmcnt(4)
	v_mov_b32_e32 v44, v16
	s_waitcnt lgkmcnt(3)
	v_mov_b32_e32 v45, v20
	s_waitcnt lgkmcnt(2)
	v_mov_b32_e32 v46, v24
	s_waitcnt lgkmcnt(1)
	v_mov_b32_e32 v47, v28
	v_mov_b32_e32 v20, v17
	v_mov_b32_e32 v28, v25
	v_mov_b32_e32 v16, v18
	v_mov_b32_e32 v17, v22
	v_mov_b32_e32 v24, v26
	v_mov_b32_e32 v25, v30
	v_mov_b32_e32 v22, v19
	v_mov_b32_e32 v30, v27
	v_add_u32_e32 v12, 16, v12
	s_waitcnt vmcnt(23)
	v_pk_fma_f32 v[8:9], v[234:235], v[44:45], v[8:9] op_sel_hi:[0,1,1]
	v_pk_fma_f32 v[10:11], v[234:235], v[46:47], v[10:11] op_sel_hi:[0,1,1]
	s_waitcnt lgkmcnt(0)
	v_fmac_f32_e32 v2, v234, v32
	s_waitcnt vmcnt(22)
	v_pk_fma_f32 v[8:9], v[234:235], v[20:21], v[8:9] op_sel:[1,0,0] op_sel_hi:[1,1,1]
	v_pk_fma_f32 v[10:11], v[234:235], v[28:29], v[10:11] op_sel:[1,0,0] op_sel_hi:[1,1,1]
	v_fmac_f32_e32 v2, v235, v33
	s_waitcnt vmcnt(21)
	v_pk_fma_f32 v[8:9], v[236:237], v[16:17], v[8:9] op_sel_hi:[0,1,1]
	v_pk_fma_f32 v[10:11], v[236:237], v[24:25], v[10:11] op_sel_hi:[0,1,1]
	v_fmac_f32_e32 v2, v236, v34
	s_waitcnt vmcnt(20)
	v_pk_fma_f32 v[8:9], v[236:237], v[22:23], v[8:9] op_sel:[1,0,0] op_sel_hi:[1,1,1]
	v_pk_fma_f32 v[10:11], v[236:237], v[30:31], v[10:11] op_sel:[1,0,0] op_sel_hi:[1,1,1]
	v_fmac_f32_e32 v2, v237, v35
	ds_read_b128 v[16:19], v12
	ds_read_b128 v[20:23], v12 offset:4096
	ds_read_b128 v[24:27], v12 offset:8192
	ds_read_b128 v[28:31], v12 offset:12288
	ds_read_b128 v[32:35], v12 offset:16384
	s_waitcnt lgkmcnt(4)
	v_mov_b32_e32 v44, v16
	s_waitcnt lgkmcnt(3)
	v_mov_b32_e32 v45, v20
	s_waitcnt lgkmcnt(2)
	v_mov_b32_e32 v46, v24
	s_waitcnt lgkmcnt(1)
	v_mov_b32_e32 v47, v28
	v_mov_b32_e32 v20, v17
	v_mov_b32_e32 v28, v25
	v_mov_b32_e32 v16, v18
	v_mov_b32_e32 v17, v22
	v_mov_b32_e32 v24, v26
	v_mov_b32_e32 v25, v30
	v_mov_b32_e32 v22, v19
	v_mov_b32_e32 v30, v27
	v_add_u32_e32 v12, 16, v12
	s_waitcnt vmcnt(19)
	v_pk_fma_f32 v[8:9], v[238:239], v[44:45], v[8:9] op_sel_hi:[0,1,1]
	v_pk_fma_f32 v[10:11], v[238:239], v[46:47], v[10:11] op_sel_hi:[0,1,1]
	s_waitcnt lgkmcnt(0)
	v_fmac_f32_e32 v2, v238, v32
	s_waitcnt vmcnt(18)
	v_pk_fma_f32 v[8:9], v[238:239], v[20:21], v[8:9] op_sel:[1,0,0] op_sel_hi:[1,1,1]
	v_pk_fma_f32 v[10:11], v[238:239], v[28:29], v[10:11] op_sel:[1,0,0] op_sel_hi:[1,1,1]
	v_fmac_f32_e32 v2, v239, v33
	s_waitcnt vmcnt(17)
	v_pk_fma_f32 v[8:9], v[240:241], v[16:17], v[8:9] op_sel_hi:[0,1,1]
	v_pk_fma_f32 v[10:11], v[240:241], v[24:25], v[10:11] op_sel_hi:[0,1,1]
	v_fmac_f32_e32 v2, v240, v34
	s_waitcnt vmcnt(16)
	v_pk_fma_f32 v[8:9], v[240:241], v[22:23], v[8:9] op_sel:[1,0,0] op_sel_hi:[1,1,1]
	v_pk_fma_f32 v[10:11], v[240:241], v[30:31], v[10:11] op_sel:[1,0,0] op_sel_hi:[1,1,1]
	v_fmac_f32_e32 v2, v241, v35
	ds_read_b128 v[16:19], v12
	ds_read_b128 v[20:23], v12 offset:4096
	ds_read_b128 v[24:27], v12 offset:8192
	ds_read_b128 v[28:31], v12 offset:12288
	ds_read_b128 v[32:35], v12 offset:16384
	s_waitcnt lgkmcnt(4)
	v_mov_b32_e32 v44, v16
	s_waitcnt lgkmcnt(3)
	v_mov_b32_e32 v45, v20
	s_waitcnt lgkmcnt(2)
	v_mov_b32_e32 v46, v24
	s_waitcnt lgkmcnt(1)
	v_mov_b32_e32 v47, v28
	v_mov_b32_e32 v20, v17
	v_mov_b32_e32 v28, v25
	v_mov_b32_e32 v16, v18
	v_mov_b32_e32 v17, v22
	v_mov_b32_e32 v24, v26
	v_mov_b32_e32 v25, v30
	v_mov_b32_e32 v22, v19
	v_mov_b32_e32 v30, v27
	v_add_u32_e32 v12, 16, v12
	s_waitcnt vmcnt(15)
	v_pk_fma_f32 v[8:9], v[242:243], v[44:45], v[8:9] op_sel_hi:[0,1,1]
	v_pk_fma_f32 v[10:11], v[242:243], v[46:47], v[10:11] op_sel_hi:[0,1,1]
	s_waitcnt lgkmcnt(0)
	v_fmac_f32_e32 v2, v242, v32
	s_waitcnt vmcnt(14)
	v_pk_fma_f32 v[8:9], v[242:243], v[20:21], v[8:9] op_sel:[1,0,0] op_sel_hi:[1,1,1]
	v_pk_fma_f32 v[10:11], v[242:243], v[28:29], v[10:11] op_sel:[1,0,0] op_sel_hi:[1,1,1]
	v_fmac_f32_e32 v2, v243, v33
	s_waitcnt vmcnt(13)
	v_pk_fma_f32 v[8:9], v[244:245], v[16:17], v[8:9] op_sel_hi:[0,1,1]
	v_pk_fma_f32 v[10:11], v[244:245], v[24:25], v[10:11] op_sel_hi:[0,1,1]
	v_fmac_f32_e32 v2, v244, v34
	s_waitcnt vmcnt(12)
	v_pk_fma_f32 v[8:9], v[244:245], v[22:23], v[8:9] op_sel:[1,0,0] op_sel_hi:[1,1,1]
	v_pk_fma_f32 v[10:11], v[244:245], v[30:31], v[10:11] op_sel:[1,0,0] op_sel_hi:[1,1,1]
	v_fmac_f32_e32 v2, v245, v35
	ds_read_b128 v[16:19], v12
	ds_read_b128 v[20:23], v12 offset:4096
	ds_read_b128 v[24:27], v12 offset:8192
	ds_read_b128 v[28:31], v12 offset:12288
	ds_read_b128 v[32:35], v12 offset:16384
	s_waitcnt lgkmcnt(4)
	v_mov_b32_e32 v44, v16
	s_waitcnt lgkmcnt(3)
	v_mov_b32_e32 v45, v20
	s_waitcnt lgkmcnt(2)
	v_mov_b32_e32 v46, v24
	s_waitcnt lgkmcnt(1)
	v_mov_b32_e32 v47, v28
	v_mov_b32_e32 v20, v17
	v_mov_b32_e32 v28, v25
	v_mov_b32_e32 v16, v18
	v_mov_b32_e32 v17, v22
	v_mov_b32_e32 v24, v26
	v_mov_b32_e32 v25, v30
	v_mov_b32_e32 v22, v19
	v_mov_b32_e32 v30, v27
	v_add_u32_e32 v12, 16, v12
	s_waitcnt vmcnt(11)
	v_pk_fma_f32 v[8:9], v[246:247], v[44:45], v[8:9] op_sel_hi:[0,1,1]
	v_pk_fma_f32 v[10:11], v[246:247], v[46:47], v[10:11] op_sel_hi:[0,1,1]
	s_waitcnt lgkmcnt(0)
	v_fmac_f32_e32 v2, v246, v32
	s_waitcnt vmcnt(10)
	v_pk_fma_f32 v[8:9], v[246:247], v[20:21], v[8:9] op_sel:[1,0,0] op_sel_hi:[1,1,1]
	v_pk_fma_f32 v[10:11], v[246:247], v[28:29], v[10:11] op_sel:[1,0,0] op_sel_hi:[1,1,1]
	v_fmac_f32_e32 v2, v247, v33
	s_waitcnt vmcnt(9)
	v_pk_fma_f32 v[8:9], v[248:249], v[16:17], v[8:9] op_sel_hi:[0,1,1]
	v_pk_fma_f32 v[10:11], v[248:249], v[24:25], v[10:11] op_sel_hi:[0,1,1]
	v_fmac_f32_e32 v2, v248, v34
	s_waitcnt vmcnt(8)
	v_pk_fma_f32 v[8:9], v[248:249], v[22:23], v[8:9] op_sel:[1,0,0] op_sel_hi:[1,1,1]
	v_pk_fma_f32 v[10:11], v[248:249], v[30:31], v[10:11] op_sel:[1,0,0] op_sel_hi:[1,1,1]
	v_fmac_f32_e32 v2, v249, v35
	ds_read_b128 v[16:19], v12
	ds_read_b128 v[20:23], v12 offset:4096
	ds_read_b128 v[24:27], v12 offset:8192
	ds_read_b128 v[28:31], v12 offset:12288
	ds_read_b128 v[32:35], v12 offset:16384
	s_waitcnt lgkmcnt(4)
	v_mov_b32_e32 v44, v16
	s_waitcnt lgkmcnt(3)
	v_mov_b32_e32 v45, v20
	s_waitcnt lgkmcnt(2)
	v_mov_b32_e32 v46, v24
	s_waitcnt lgkmcnt(1)
	v_mov_b32_e32 v47, v28
	v_mov_b32_e32 v20, v17
	v_mov_b32_e32 v28, v25
	v_mov_b32_e32 v16, v18
	v_mov_b32_e32 v17, v22
	v_mov_b32_e32 v24, v26
	v_mov_b32_e32 v25, v30
	v_mov_b32_e32 v22, v19
	v_mov_b32_e32 v30, v27
	v_add_u32_e32 v12, 16, v12
	s_waitcnt vmcnt(7)
	v_pk_fma_f32 v[8:9], v[210:211], v[44:45], v[8:9] op_sel_hi:[0,1,1]
	v_pk_fma_f32 v[10:11], v[210:211], v[46:47], v[10:11] op_sel_hi:[0,1,1]
	s_waitcnt lgkmcnt(0)
	v_fmac_f32_e32 v2, v210, v32
	s_waitcnt vmcnt(6)
	v_pk_fma_f32 v[8:9], v[210:211], v[20:21], v[8:9] op_sel:[1,0,0] op_sel_hi:[1,1,1]
	v_pk_fma_f32 v[10:11], v[210:211], v[28:29], v[10:11] op_sel:[1,0,0] op_sel_hi:[1,1,1]
	v_fmac_f32_e32 v2, v211, v33
	s_waitcnt vmcnt(5)
	v_pk_fma_f32 v[8:9], v[212:213], v[16:17], v[8:9] op_sel_hi:[0,1,1]
	v_pk_fma_f32 v[10:11], v[212:213], v[24:25], v[10:11] op_sel_hi:[0,1,1]
	v_fmac_f32_e32 v2, v212, v34
	s_waitcnt vmcnt(4)
	v_pk_fma_f32 v[8:9], v[212:213], v[22:23], v[8:9] op_sel:[1,0,0] op_sel_hi:[1,1,1]
	v_pk_fma_f32 v[10:11], v[212:213], v[30:31], v[10:11] op_sel:[1,0,0] op_sel_hi:[1,1,1]
	v_fmac_f32_e32 v2, v213, v35
	ds_read_b128 v[16:19], v12
	ds_read_b128 v[20:23], v12 offset:4096
	ds_read_b128 v[24:27], v12 offset:8192
	ds_read_b128 v[28:31], v12 offset:12288
	ds_read_b128 v[32:35], v12 offset:16384
	s_waitcnt lgkmcnt(4)
	v_mov_b32_e32 v44, v16
	s_waitcnt lgkmcnt(3)
	v_mov_b32_e32 v45, v20
	s_waitcnt lgkmcnt(2)
	v_mov_b32_e32 v46, v24
	s_waitcnt lgkmcnt(1)
	v_mov_b32_e32 v47, v28
	v_mov_b32_e32 v20, v17
	v_mov_b32_e32 v28, v25
	v_mov_b32_e32 v16, v18
	v_mov_b32_e32 v17, v22
	v_mov_b32_e32 v24, v26
	v_mov_b32_e32 v25, v30
	v_mov_b32_e32 v22, v19
	v_mov_b32_e32 v30, v27
	v_add_u32_e32 v12, 16, v12
	s_waitcnt vmcnt(3)
	v_pk_fma_f32 v[8:9], v[214:215], v[44:45], v[8:9] op_sel_hi:[0,1,1]
	v_pk_fma_f32 v[10:11], v[214:215], v[46:47], v[10:11] op_sel_hi:[0,1,1]
	s_waitcnt lgkmcnt(0)
	v_fmac_f32_e32 v2, v214, v32
	s_waitcnt vmcnt(2)
	v_pk_fma_f32 v[8:9], v[214:215], v[20:21], v[8:9] op_sel:[1,0,0] op_sel_hi:[1,1,1]
	v_pk_fma_f32 v[10:11], v[214:215], v[28:29], v[10:11] op_sel:[1,0,0] op_sel_hi:[1,1,1]
	v_fmac_f32_e32 v2, v215, v33
	s_waitcnt vmcnt(1)
	v_pk_fma_f32 v[8:9], v[216:217], v[16:17], v[8:9] op_sel_hi:[0,1,1]
	v_pk_fma_f32 v[10:11], v[216:217], v[24:25], v[10:11] op_sel_hi:[0,1,1]
	v_fmac_f32_e32 v2, v216, v34
	s_waitcnt vmcnt(0)
	v_pk_fma_f32 v[8:9], v[216:217], v[22:23], v[8:9] op_sel:[1,0,0] op_sel_hi:[1,1,1]
	v_pk_fma_f32 v[10:11], v[216:217], v[30:31], v[10:11] op_sel:[1,0,0] op_sel_hi:[1,1,1]
	v_fmac_f32_e32 v2, v217, v35
	s_movk_i32 s8, 0x280
	v_mul_lo_u32 v6, v1, s8
	v_lshl_or_b32 v6, v4, 2, v6
	s_movk_i32 s8, 0xa0
	v_add_u32_e32 v7, 0x5000, v6
	v_cmp_gt_i32_e32 vcc, s8, v15
	ds_write2_b32 v7, v8, v9 offset1:32
	ds_write2_b32 v7, v10, v11 offset0:64 offset1:96
	ds_write_b32 v6, v2 offset:20992
	s_waitcnt lgkmcnt(0)
	s_barrier
	s_and_saveexec_b64 s[8:9], vcc
	s_cbranch_execz .LBB0_56
	s_load_dwordx16 s[12:27], s[86:87], 0x40
	s_and_b64 s[10:11], s[6:7], exec
	s_cselect_b32 s10, 0xc00, 0
	s_add_i32 s10, s4, s10
	v_or_b32_e32 v2, s10, v4
	s_waitcnt lgkmcnt(0)
	v_lshl_add_u64 v[6:7], v[2:3], 2, s[18:19]
	global_load_dword v15, v[6:7], off
	s_load_dwordx16 s[12:27], s[86:87], 0x100
	s_and_b64 s[6:7], s[6:7], exec
	v_lshlrev_b32_e32 v2, 2, v4
	s_cselect_b32 s6, 5, 0
	v_add_u32_e32 v4, v2, v5
	s_waitcnt lgkmcnt(0)
	v_mov_b64_e32 v[6:7], s[20:21]
	v_add_u32_e32 v1, s6, v1
	v_add_u32_e32 v8, 0x5000, v4
	v_add_u32_e32 v9, 0x5400, v4
	v_add_u32_e32 v10, 0x5a00, v4
	v_add_u32_e32 v12, 0x5e00, v4
	v_mad_i64_i32 v[4:5], s[6:7], v1, s40, v[6:7]
	ds_read2_b32 v[6:7], v8 offset1:160
	ds_read2_b32 v[8:9], v9 offset0:64 offset1:224
	ds_read2_b32 v[10:11], v10 offset1:160
	ds_read2_b32 v[12:13], v12 offset0:64 offset1:224
	v_lshl_add_u64 v[4:5], s[4:5], 2, v[4:5]
	v_lshl_add_u64 v[4:5], v[4:5], 0, v[2:3]
	s_waitcnt vmcnt(0) lgkmcnt(3)
	v_add_f32_e32 v1, v15, v6
	v_add_f32_e32 v1, v1, v7
	s_waitcnt lgkmcnt(2)
	v_add_f32_e32 v1, v1, v8
	v_add_f32_e32 v1, v1, v9
	s_waitcnt lgkmcnt(1)
	v_add_f32_e32 v1, v1, v10
	v_add_f32_e32 v1, v1, v11
	s_waitcnt lgkmcnt(0)
	v_add_f32_e32 v1, v1, v12
	v_add_f32_e32 v1, v1, v13
	global_store_dword v[4:5], v1, off

.LBB0_372:
	s_mul_hi_i32 s0, s43, 0x55555556
	s_lshr_b32 s1, s0, 31
	s_add_i32 s0, s0, s1
	s_lshl_b32 s12, s0, 7
	s_mul_i32 s0, s0, 3
	s_sub_i32 s0, s43, s0
	v_mov_b32_e32 v1, v0
	s_lshl_b32 s44, s0, 3
	s_add_i32 s44, s44, s41
	s_waitcnt vmcnt(4)
	v_ashrrev_i32_e32 v8, 3, v1
	v_and_b32_e32 v9, 7, v1
	v_add_u32_e32 v4, s12, v8
	v_mov_b64_e32 v[2:3], s[66:67]
	s_lshl_b32 s13, s44, 7
	v_mad_i64_i32 v[2:3], s[0:1], v4, s58, v[2:3]
	v_lshlrev_b32_e32 v106, 4, v9
	v_lshl_add_u64 v[98:99], v[2:3], 0, v[106:107]
	v_add_u32_e32 v4, s13, v8
	v_mov_b64_e32 v[2:3], s[2:3]
	v_mad_i64_i32 v[2:3], s[0:1], v4, s58, v[2:3]
	s_mov_b32 s0, 0x11000
	s_nop 0
	v_add_co_u32_e32 v4, vcc, s0, v98
	s_mov_b32 s1, 0x22000
	s_nop 0
	v_addc_co_u32_e32 v5, vcc, 0, v99, vcc
	v_add_co_u32_e32 v6, vcc, s1, v98
	s_mov_b32 s4, 0x33000
	s_nop 0
	v_addc_co_u32_e32 v7, vcc, 0, v99, vcc
	global_load_dwordx4 v[62:65], v[98:99], off
	global_load_dwordx4 v[70:73], v[4:5], off
	global_load_dwordx4 v[74:77], v[6:7], off
	v_add_co_u32_e32 v4, vcc, s4, v98
	v_lshl_add_u64 v[100:101], v[2:3], 0, v[106:107]
	s_nop 0
	v_addc_co_u32_e32 v5, vcc, 0, v99, vcc
	v_add_co_u32_e32 v2, vcc, s0, v100
	global_load_dwordx4 v[78:81], v[4:5], off
	s_nop 0
	v_addc_co_u32_e32 v3, vcc, 0, v101, vcc
	v_add_co_u32_e32 v4, vcc, s1, v100
	global_load_dwordx4 v[82:85], v[100:101], off
	s_nop 0
	v_addc_co_u32_e32 v5, vcc, 0, v101, vcc
	global_load_dwordx4 v[86:89], v[2:3], off
	global_load_dwordx4 v[90:93], v[4:5], off
	v_add_co_u32_e32 v2, vcc, s4, v100
	v_lshrrev_b32_e32 v4, 5, v1
	s_nop 0
	v_addc_co_u32_e32 v3, vcc, 0, v101, vcc
	global_load_dwordx4 v[94:97], v[2:3], off
	v_ashrrev_i32_e32 v3, 4, v1
	s_waitcnt vmcnt(11)
	v_xor_b32_e32 v10, v3, v1
	v_and_b32_e32 v3, 1, v3
	v_and_b32_e32 v4, 6, v4
	v_lshrrev_b32_e32 v2, 4, v1
	v_bfe_u32 v102, v1, 4, 2
	v_bfe_u32 v5, v1, 1, 3
	v_bitop3_b32 v3, v3, v9, v4 bitop3:0x36
	v_ashrrev_i32_e32 v103, 7, v1
	v_lshlrev_b32_e32 v105, 7, v8
	v_bitop3_b32 v2, v2, v5, 3 bitop3:0x6c
	v_bitop3_b32 v5, v102, v5, 4 bitop3:0x36
	v_lshlrev_b32_e32 v4, 4, v10
	s_movk_i32 s0, 0x70
	v_lshlrev_b32_e32 v111, 4, v3
	v_and_b32_e32 v104, 15, v1
	v_lshlrev_b32_e32 v6, 1, v1
	v_and_b32_e32 v7, 0x43, v1
	v_lshlrev_b32_e32 v8, 13, v103
	v_lshlrev_b32_e32 v106, 4, v2
	v_lshlrev_b32_e32 v109, 4, v5
	v_and_or_b32 v110, v4, s0, v105
	v_or_b32_e32 v2, v105, v111
	v_lshlrev_b32_e32 v11, 7, v104
	v_and_or_b32 v6, v6, 24, v7
	v_or_b32_e32 v3, v106, v8
	v_or_b32_e32 v4, v109, v8
	v_lshlrev_b32_e32 v108, 7, v6
	s_mov_b64 s[0:1], 0
	v_lshl_add_u64 v[224:225], v[98:99], 0, s[0:1]
	global_load_dwordx4 v[224:227], v[224:225], off offset:128
	s_add_u32 s6, s0, 0x11000
	s_addc_u32 s7, s1, 0
	v_lshl_add_u64 v[228:229], v[98:99], 0, s[6:7]
	global_load_dwordx4 v[228:231], v[228:229], off offset:128
	s_add_u32 vcc_lo, s0, 0x22000
	s_addc_u32 vcc_hi, s1, 0
	v_lshl_add_u64 v[232:233], v[98:99], 0, vcc
	global_load_dwordx4 v[232:235], v[232:233], off offset:128
	s_add_u32 s6, s0, 0x33000
	s_addc_u32 s7, s1, 0
	v_lshl_add_u64 v[236:237], v[98:99], 0, s[6:7]
	global_load_dwordx4 v[236:239], v[236:237], off offset:128
	v_lshl_add_u64 v[240:241], v[100:101], 0, s[0:1]
	global_load_dwordx4 v[240:243], v[240:241], off offset:128
	s_add_u32 vcc_lo, s0, 0x11000
	s_addc_u32 vcc_hi, s1, 0
	v_lshl_add_u64 v[244:245], v[100:101], 0, vcc
	global_load_dwordx4 v[244:247], v[244:245], off offset:128
	s_add_u32 s6, s0, 0x22000
	s_addc_u32 s7, s1, 0
	v_lshl_add_u64 v[248:249], v[100:101], 0, s[6:7]
	global_load_dwordx4 v[248:251], v[248:249], off offset:128
	s_add_u32 vcc_lo, s0, 0x33000
	s_addc_u32 vcc_hi, s1, 0
	v_lshl_add_u64 v[252:253], v[100:101], 0, vcc
	global_load_dwordx4 v[252:255], v[252:253], off offset:128
	v_add_u32_e32 v112, v3, v11
	v_add_u32_e32 v113, v4, v11
	s_waitcnt vmcnt(15)
	ds_write_b128 v110, v[62:65]
	s_waitcnt vmcnt(14)
	ds_write_b128 v110, v[70:73] offset:4096
	s_waitcnt vmcnt(13)
	ds_write_b128 v110, v[74:77] offset:8192
	s_waitcnt vmcnt(12)
	ds_write_b128 v110, v[78:81] offset:12288
	s_waitcnt vmcnt(11)
	ds_write_b128 v2, v[82:85] offset:16384
	s_waitcnt vmcnt(10)
	ds_write_b128 v2, v[86:89] offset:20480
	s_waitcnt vmcnt(9)
	ds_write_b128 v2, v[90:93] offset:24576
	s_waitcnt vmcnt(8)
	ds_write_b128 v2, v[94:97] offset:28672
	v_mov_b32_e32 v2, 0
	v_mov_b32_e32 v3, v2
	v_mov_b32_e32 v4, v2
	v_mov_b32_e32 v5, v2
	v_mov_b32_e32 v6, v2
	v_mov_b32_e32 v7, v2
	v_mov_b32_e32 v8, v2
	v_mov_b32_e32 v9, v2
	v_mov_b32_e32 v10, v2
	v_mov_b32_e32 v11, v2
	v_mov_b32_e32 v12, v2
	v_mov_b32_e32 v13, v2
	v_mov_b32_e32 v14, v2
	v_mov_b32_e32 v15, v2
	v_mov_b32_e32 v16, v2
	v_mov_b32_e32 v17, v2
	v_mov_b32_e32 v18, v2
	v_mov_b32_e32 v19, v2
	v_mov_b32_e32 v20, v2
	v_mov_b32_e32 v21, v2
	v_mov_b32_e32 v22, v2
	v_mov_b32_e32 v23, v2
	v_mov_b32_e32 v24, v2
	v_mov_b32_e32 v25, v2
	v_mov_b32_e32 v26, v2
	v_mov_b32_e32 v27, v2
	v_mov_b32_e32 v28, v2
	v_mov_b32_e32 v29, v2
	v_mov_b32_e32 v30, v2
	v_mov_b32_e32 v31, v2
	v_mov_b32_e32 v32, v2
	v_mov_b32_e32 v33, v2
	v_mov_b32_e32 v34, v2
	v_mov_b32_e32 v35, v2
	v_mov_b32_e32 v36, v2
	v_mov_b32_e32 v37, v2
	v_mov_b32_e32 v38, v2
	v_mov_b32_e32 v39, v2
	v_mov_b32_e32 v40, v2
	v_mov_b32_e32 v41, v2
	v_mov_b32_e32 v42, v2
	v_mov_b32_e32 v43, v2
	v_mov_b32_e32 v44, v2
	v_mov_b32_e32 v45, v2
	v_mov_b32_e32 v46, v2
	v_mov_b32_e32 v47, v2
	v_mov_b32_e32 v48, v2
	v_mov_b32_e32 v49, v2
	v_mov_b32_e32 v50, v2
	v_mov_b32_e32 v51, v2
	v_mov_b32_e32 v52, v2
	v_mov_b32_e32 v53, v2
	v_mov_b32_e32 v54, v2
	v_mov_b32_e32 v55, v2
	v_mov_b32_e32 v56, v2
	v_mov_b32_e32 v57, v2
	v_mov_b32_e32 v58, v2
	v_mov_b32_e32 v59, v2
	v_mov_b32_e32 v60, v2
	v_mov_b32_e32 v61, v2
	v_mov_b32_e32 v66, v2
	v_mov_b32_e32 v67, v2
	v_mov_b32_e32 v68, v2
	v_mov_b32_e32 v69, v2
	v_add_u32_e32 v188, v106, v108
	v_add_u32_e32 v189, v109, v108
	v_add_u32_e32 v190, v105, v111
	s_waitcnt lgkmcnt(0)
	s_barrier
	s_branch .LBB0_374

.LBB0_521:
	s_cmp_lt_i32 s41, 6
	s_cbranch_scc0 .LBB0_203
	s_lshl_b32 s0, s41, 6
	s_and_b32 s0, s0, 64
	s_add_i32 s12, s42, s0
	v_mov_b32_e32 v1, v0
	s_lshl_b32 s13, s12, 6
	s_ashr_i32 s41, s41, 1
	s_lshl_b32 s14, s41, 7
	s_waitcnt vmcnt(4)
	v_ashrrev_i32_e32 v8, 3, v1
	v_and_b32_e32 v9, 7, v1
	v_add_u32_e32 v4, s13, v8
	v_mov_b64_e32 v[2:3], s[66:67]
	s_addk_i32 s14, 0xc00
	v_mad_i64_i32 v[2:3], s[0:1], v4, s58, v[2:3]
	v_lshlrev_b32_e32 v106, 4, v9
	v_lshl_add_u64 v[58:59], v[2:3], 0, v[106:107]
	v_add_u32_e32 v4, s14, v8
	v_mov_b64_e32 v[2:3], s[2:3]
	v_mad_i64_i32 v[2:3], s[0:1], v4, s58, v[2:3]
	s_mov_b32 s0, 0x11000
	s_nop 0
	v_add_co_u32_e32 v4, vcc, s0, v58
	v_lshl_add_u64 v[60:61], v[2:3], 0, v[106:107]
	s_nop 0
	v_addc_co_u32_e32 v5, vcc, 0, v59, vcc
	v_add_co_u32_e32 v2, vcc, s0, v60
	s_mov_b32 s0, 0x22000
	s_nop 0
	v_addc_co_u32_e32 v3, vcc, 0, v61, vcc
	v_add_co_u32_e32 v6, vcc, s0, v60
	s_mov_b32 s0, 0x33000
	s_nop 0
	v_addc_co_u32_e32 v7, vcc, 0, v61, vcc
	global_load_dwordx4 v[34:37], v[58:59], off
	global_load_dwordx4 v[38:41], v[60:61], off
	global_load_dwordx4 v[42:45], v[2:3], off
	global_load_dwordx4 v[50:53], v[6:7], off
	v_add_co_u32_e32 v2, vcc, s0, v60
	s_waitcnt vmcnt(7)
	v_ashrrev_i32_e32 v11, 4, v1
	v_addc_co_u32_e32 v3, vcc, 0, v61, vcc
	global_load_dwordx4 v[54:57], v[2:3], off
	global_load_dwordx4 v[46:49], v[4:5], off
	v_lshrrev_b32_e32 v12, 5, v1
	v_lshrrev_b32_e32 v10, 4, v1
	v_bfe_u32 v62, v1, 4, 2
	v_bfe_u32 v13, v1, 1, 3
	s_waitcnt vmcnt(8)
	v_xor_b32_e32 v16, v11, v1
	v_and_b32_e32 v11, 1, v11
	v_and_b32_e32 v12, 6, v12
	v_ashrrev_i32_e32 v63, 7, v1
	v_lshlrev_b32_e32 v65, 7, v8
	v_bitop3_b32 v8, v10, v13, 3 bitop3:0x6c
	v_bitop3_b32 v13, v62, v13, 4 bitop3:0x36
	v_bitop3_b32 v9, v11, v9, v12 bitop3:0x36
	v_and_b32_e32 v64, 15, v1
	v_lshlrev_b32_e32 v14, 1, v1
	v_and_b32_e32 v15, 0x43, v1
	v_lshlrev_b32_e32 v10, 12, v63
	v_lshlrev_b32_e32 v66, 4, v8
	v_lshlrev_b32_e32 v68, 4, v13
	v_lshlrev_b32_e32 v70, 4, v9
	v_mov_b32_e32 v2, 0
	v_lshlrev_b32_e32 v17, 7, v64
	v_and_or_b32 v14, v14, 24, v15
	v_lshlrev_b32_e32 v11, 4, v16
	s_movk_i32 s4, 0x70
	v_or_b32_e32 v8, v66, v10
	v_or_b32_e32 v9, v68, v10
	v_or_b32_e32 v10, v65, v70
	s_mov_b64 s[0:1], 0
	v_lshl_add_u64 v[224:225], v[58:59], 0, s[0:1]
	global_load_dwordx4 v[224:227], v[224:225], off offset:128
	s_add_u32 s6, s0, 0x11000
	s_addc_u32 s7, s1, 0
	v_lshl_add_u64 v[228:229], v[58:59], 0, s[6:7]
	global_load_dwordx4 v[228:231], v[228:229], off offset:128
	v_lshl_add_u64 v[232:233], v[60:61], 0, s[0:1]
	global_load_dwordx4 v[232:235], v[232:233], off offset:128
	s_add_u32 vcc_lo, s0, 0x11000
	s_addc_u32 vcc_hi, s1, 0
	v_lshl_add_u64 v[236:237], v[60:61], 0, vcc
	global_load_dwordx4 v[236:239], v[236:237], off offset:128
	s_add_u32 s6, s0, 0x22000
	s_addc_u32 s7, s1, 0
	v_lshl_add_u64 v[240:241], v[60:61], 0, s[6:7]
	global_load_dwordx4 v[240:243], v[240:241], off offset:128
	s_add_u32 vcc_lo, s0, 0x33000
	s_addc_u32 vcc_hi, s1, 0
	v_lshl_add_u64 v[244:245], v[60:61], 0, vcc
	global_load_dwordx4 v[244:247], v[244:245], off offset:128
	v_mov_b32_e32 v3, v2
	v_mov_b32_e32 v4, v2
	v_mov_b32_e32 v5, v2
	v_mov_b32_e32 v6, v2
	v_mov_b32_e32 v7, v2
	v_lshlrev_b32_e32 v67, 7, v14
	v_and_or_b32 v69, v11, s4, v65
	v_add_u32_e32 v71, v8, v17
	v_add_u32_e32 v72, v9, v17
	v_mov_b32_e32 v8, v2
	v_mov_b32_e32 v9, v2
	v_mov_b32_e32 v11, v2
	v_mov_b32_e32 v12, v2
	v_mov_b32_e32 v13, v2
	v_mov_b32_e32 v14, v2
	v_mov_b32_e32 v15, v2
	v_mov_b32_e32 v16, v2
	v_mov_b32_e32 v17, v2
	v_mov_b32_e32 v18, v2
	v_mov_b32_e32 v19, v2
	v_mov_b32_e32 v20, v2
	v_mov_b32_e32 v21, v2
	v_mov_b32_e32 v22, v2
	s_waitcnt vmcnt(10)
	ds_write_b128 v10, v[38:41] offset:16384
	ds_write_b128 v69, v[34:37]
	s_waitcnt vmcnt(9)
	ds_write_b128 v10, v[42:45] offset:20480
	s_waitcnt vmcnt(8)
	ds_write_b128 v10, v[50:53] offset:24576
	s_waitcnt vmcnt(7)
	ds_write_b128 v10, v[54:57] offset:28672
	s_waitcnt vmcnt(6)
	ds_write_b128 v69, v[46:49] offset:4096
	v_mov_b32_e32 v10, v2
	v_mov_b32_e32 v23, v2
	v_mov_b32_e32 v24, v2
	v_mov_b32_e32 v25, v2
	v_mov_b32_e32 v26, v2
	v_mov_b32_e32 v27, v2
	v_mov_b32_e32 v28, v2
	v_mov_b32_e32 v29, v2
	v_mov_b32_e32 v30, v2
	v_mov_b32_e32 v31, v2
	v_mov_b32_e32 v32, v2
	v_mov_b32_e32 v33, v2
	v_add_u32_e32 v188, v66, v67
	v_add_u32_e32 v189, v68, v67
	v_add_u32_e32 v190, v65, v70
	s_waitcnt lgkmcnt(0)
	s_barrier
	s_branch .LBB0_524

.LBB0_1384:
	s_abs_i32 s11, s39
	s_mul_hi_u32 s12, s11, s46
	s_mul_i32 s13, s12, s43
	s_ashr_i32 s10, s39, 31
	s_sub_i32 s11, s11, s13
	s_xor_b32 s10, s10, s45
	s_add_i32 s13, s12, 1
	s_sub_i32 s14, s11, s43
	s_cmp_ge_u32 s11, s43
	s_cselect_b32 s12, s13, s12
	s_cselect_b32 s11, s14, s11
	s_add_i32 s13, s12, 1
	s_cmp_ge_u32 s11, s43
	s_cselect_b32 s11, s13, s12
	s_xor_b32 s11, s11, s10
	s_sub_i32 s10, s11, s10
	v_mov_b32_e32 v1, v0
	s_lshl_b32 s47, s10, 7
	s_mul_i32 s10, s10, s40
	s_sub_i32 s10, s39, s10
	s_waitcnt vmcnt(1)
	v_ashrrev_i32_e32 v34, 3, v1
	v_and_b32_e32 v35, 7, v1
	v_add_u32_e32 v4, s47, v34
	v_mov_b64_e32 v[2:3], s[66:67]
	s_lshl_b32 s48, s10, 10
	v_mad_i64_i32 v[2:3], s[10:11], v4, s58, v[2:3]
	v_lshlrev_b32_e32 v106, 4, v35
	v_lshl_add_u64 v[98:99], v[2:3], 0, v[106:107]
	s_mov_b32 s4, 0x11000
	v_add_co_u32_e32 v6, vcc, s4, v98
	s_mov_b32 s5, 0x22000
	s_nop 0
	v_addc_co_u32_e32 v7, vcc, 0, v99, vcc
	s_add_i32 s48, s48, s44
	v_add_co_u32_e32 v10, vcc, s5, v98
	v_add_u32_e32 v4, s48, v34
	v_mov_b64_e32 v[2:3], s[0:1]
	v_addc_co_u32_e32 v11, vcc, 0, v99, vcc
	s_mov_b32 s8, 0x33000
	v_mad_i64_i32 v[18:19], s[10:11], v4, s58, v[2:3]
	v_add_co_u32_e32 v14, vcc, s8, v98
	v_lshl_add_u64 v[100:101], v[18:19], 0, v[106:107]
	s_nop 0
	v_addc_co_u32_e32 v15, vcc, 0, v99, vcc
	v_add_co_u32_e32 v22, vcc, s4, v100
	global_load_dwordx4 v[2:5], v[98:99], off
	s_nop 0
	v_addc_co_u32_e32 v23, vcc, 0, v101, vcc
	v_add_co_u32_e32 v26, vcc, s5, v100
	global_load_dwordx4 v[6:9], v[6:7], off
	s_nop 0
	global_load_dwordx4 v[10:13], v[10:11], off
	v_addc_co_u32_e32 v27, vcc, 0, v101, vcc
	global_load_dwordx4 v[14:17], v[14:15], off
	v_add_co_u32_e32 v30, vcc, s8, v100
	global_load_dwordx4 v[18:21], v[100:101], off
	s_nop 0
	global_load_dwordx4 v[22:25], v[22:23], off
	s_nop 0
	global_load_dwordx4 v[26:29], v[26:27], off
	v_addc_co_u32_e32 v31, vcc, 0, v101, vcc
	global_load_dwordx4 v[30:33], v[30:31], off
	v_ashrrev_i32_e32 v37, 4, v1
	s_waitcnt vmcnt(8)
	v_lshrrev_b32_e32 v38, 5, v1
	v_xor_b32_e32 v41, v37, v1
	v_and_b32_e32 v37, 1, v37
	v_and_b32_e32 v38, 6, v38
	v_lshrrev_b32_e32 v36, 4, v1
	v_bfe_u32 v39, v1, 1, 3
	v_bitop3_b32 v35, v37, v35, v38 bitop3:0x36
	v_lshlrev_b32_e32 v105, 7, v34
	v_bitop3_b32 v34, v36, v39, 3 bitop3:0x6c
	v_lshlrev_b32_e32 v37, 4, v41
	s_movk_i32 s4, 0x70
	v_lshlrev_b32_e32 v109, 4, v35
	v_lshlrev_b32_e32 v106, 4, v34
	v_and_or_b32 v108, v37, s4, v105
	v_or_b32_e32 v34, v105, v109
	v_lshlrev_b32_e32 v40, 1, v1
	v_bfe_u32 v102, v1, 4, 2
	v_ashrrev_i32_e32 v103, 7, v1
	v_and_b32_e32 v104, 15, v1
	v_lshlrev_b32_e32 v36, 13, v103
	v_lshlrev_b32_e32 v42, 7, v104
	v_or_b32_e32 v35, v106, v36
	s_mov_b64 s[10:11], 0
	v_lshl_add_u64 v[224:225], v[98:99], 0, s[10:11]
	global_load_dwordx4 v[224:227], v[224:225], off offset:128
	s_add_u32 s28, s10, 0x11000
	s_addc_u32 s29, s11, 0
	v_lshl_add_u64 v[228:229], v[98:99], 0, s[28:29]
	global_load_dwordx4 v[228:231], v[228:229], off offset:128
	s_add_u32 vcc_lo, s10, 0x22000
	s_addc_u32 vcc_hi, s11, 0
	v_lshl_add_u64 v[232:233], v[98:99], 0, vcc
	global_load_dwordx4 v[232:235], v[232:233], off offset:128
	s_add_u32 s28, s10, 0x33000
	s_addc_u32 s29, s11, 0
	v_lshl_add_u64 v[236:237], v[98:99], 0, s[28:29]
	global_load_dwordx4 v[236:239], v[236:237], off offset:128
	v_lshl_add_u64 v[240:241], v[100:101], 0, s[10:11]
	global_load_dwordx4 v[240:243], v[240:241], off offset:128
	s_add_u32 vcc_lo, s10, 0x11000
	s_addc_u32 vcc_hi, s11, 0
	v_lshl_add_u64 v[244:245], v[100:101], 0, vcc
	global_load_dwordx4 v[244:247], v[244:245], off offset:128
	s_add_u32 s28, s10, 0x22000
	s_addc_u32 s29, s11, 0
	v_lshl_add_u64 v[248:249], v[100:101], 0, s[28:29]
	global_load_dwordx4 v[248:251], v[248:249], off offset:128
	s_add_u32 vcc_lo, s10, 0x33000
	s_addc_u32 vcc_hi, s11, 0
	v_lshl_add_u64 v[252:253], v[100:101], 0, vcc
	global_load_dwordx4 v[252:255], v[252:253], off offset:128
	v_add_u32_e32 v112, v35, v42
	s_waitcnt vmcnt(15)
	ds_write_b128 v108, v[2:5]
	s_waitcnt vmcnt(14)
	ds_write_b128 v108, v[6:9] offset:4096
	s_waitcnt vmcnt(13)
	ds_write_b128 v108, v[10:13] offset:8192
	s_waitcnt vmcnt(12)
	ds_write_b128 v108, v[14:17] offset:12288
	s_waitcnt vmcnt(11)
	ds_write_b128 v34, v[18:21] offset:16384
	s_waitcnt vmcnt(10)
	ds_write_b128 v34, v[22:25] offset:20480
	s_waitcnt vmcnt(9)
	ds_write_b128 v34, v[26:29] offset:24576
	s_waitcnt vmcnt(8)
	ds_write_b128 v34, v[30:33] offset:28672
	v_and_b32_e32 v34, 0x43, v1
	v_and_or_b32 v34, v40, 24, v34
	v_lshlrev_b32_e32 v110, 7, v34
	v_bitop3_b32 v34, v102, v39, 4 bitop3:0x36
	v_lshlrev_b32_e32 v111, 4, v34
	v_or_b32_e32 v36, v111, v36
	v_mov_b32_e32 v34, 0
	v_add_u32_e32 v113, v36, v42
	v_mov_b32_e32 v35, v34
	v_mov_b32_e32 v36, v34
	v_mov_b32_e32 v37, v34
	v_mov_b32_e32 v38, v34
	v_mov_b32_e32 v39, v34
	v_mov_b32_e32 v40, v34
	v_mov_b32_e32 v41, v34
	v_mov_b32_e32 v42, v34
	v_mov_b32_e32 v43, v34
	v_mov_b32_e32 v44, v34
	v_mov_b32_e32 v45, v34
	v_mov_b32_e32 v46, v34
	v_mov_b32_e32 v47, v34
	v_mov_b32_e32 v48, v34
	v_mov_b32_e32 v49, v34
	v_mov_b32_e32 v50, v34
	v_mov_b32_e32 v51, v34
	v_mov_b32_e32 v52, v34
	v_mov_b32_e32 v53, v34
	v_mov_b32_e32 v54, v34
	v_mov_b32_e32 v55, v34
	v_mov_b32_e32 v56, v34
	v_mov_b32_e32 v57, v34
	v_mov_b32_e32 v58, v34
	v_mov_b32_e32 v59, v34
	v_mov_b32_e32 v60, v34
	v_mov_b32_e32 v61, v34
	v_mov_b32_e32 v62, v34
	v_mov_b32_e32 v63, v34
	v_mov_b32_e32 v64, v34
	v_mov_b32_e32 v65, v34
	v_mov_b32_e32 v66, v34
	v_mov_b32_e32 v67, v34
	v_mov_b32_e32 v68, v34
	v_mov_b32_e32 v69, v34
	v_mov_b32_e32 v70, v34
	v_mov_b32_e32 v71, v34
	v_mov_b32_e32 v72, v34
	v_mov_b32_e32 v73, v34
	v_mov_b32_e32 v74, v34
	v_mov_b32_e32 v75, v34
	v_mov_b32_e32 v76, v34
	v_mov_b32_e32 v77, v34
	v_mov_b32_e32 v78, v34
	v_mov_b32_e32 v79, v34
	v_mov_b32_e32 v80, v34
	v_mov_b32_e32 v81, v34
	v_mov_b32_e32 v82, v34
	v_mov_b32_e32 v83, v34
	v_mov_b32_e32 v84, v34
	v_mov_b32_e32 v85, v34
	v_mov_b32_e32 v86, v34
	v_mov_b32_e32 v87, v34
	v_mov_b32_e32 v88, v34
	v_mov_b32_e32 v89, v34
	v_mov_b32_e32 v90, v34
	v_mov_b32_e32 v91, v34
	v_mov_b32_e32 v92, v34
	v_mov_b32_e32 v93, v34
	v_mov_b32_e32 v94, v34
	v_mov_b32_e32 v95, v34
	v_mov_b32_e32 v96, v34
	v_mov_b32_e32 v97, v34
	v_add_u32_e32 v188, v106, v110
	v_add_u32_e32 v189, v111, v110
	v_add_u32_e32 v190, v105, v109
	s_waitcnt lgkmcnt(0)
	s_barrier
	s_branch .LBB0_1386
